# moba_own (partials-merging copy): 15 chained gate loads issued together, destinations re-homed, waits recounted
# speedup vs baseline: 1.0010x; 1.0010x over previous
; __device__ __forceinline__ float bf_lo(unsigned u) { return __uint_as_float(u << 16); }
; __device__ __forceinline__ float bf_hi(unsigned u) { return __uint_as_float(u & 0xffff0000u); }
; __device__ __forceinline__ void moba_own_item(LAS unsigned char* lds, const Ptrs& P, int b, int h, int j) {
;     ...
;     float lown = l + __shfl_xor(l, 32);
;     float Mx = m;
; #pragma unroll
;     for (int k = 0; k < 3; ++k) if (k < nsel) Mx = fmaxf(Mx, mk[k]);
;     const float wo = __builtin_amdgcn_exp2f(m - Mx); float L = lown * wo;
; #pragma unroll
;     for (int dt = 0; dt < 4; ++dt) o[dt] *= wo;
; #pragma unroll
;     for (int k = 0; k < 3; ++k) if (k < nsel) { const float wk = lk[k] * __builtin_amdgcn_exp2f(mk[k] - Mx); L += wk;
;         const bf16_t* po = P.PO() + (slot0 + k) * 128;
; #pragma unroll
;         for (int dt = 0; dt < 4; ++dt)
; #pragma unroll
;             for (int g4 = 0; g4 < 4; ++g4) { const u32x2 w = *(const u32x2*)(po + 32 * dt + 8 * g4 + 4 * hi);
;                 o[dt][4 * g4] += wk * bf_lo(w.x); o[dt][4 * g4 + 1] += wk * bf_hi(w.x); o[dt][4 * g4 + 2] += wk * bf_lo(w.y); o[dt][4 * g4 + 3] += wk * bf_hi(w.y); } }
.LBB0_1017:
	v_mov_b32_e32 v141, v1
	v_lshl_add_u64 v[66:67], s[22:23], 0, v[140:141]
	v_mad_u64_u32 v[66:67], s[0:1], v142, s55, v[66:67]
	v_mad_i32_i24 v67, v143, s55, v67
	global_load_dwordx2 v[68:69], v[66:67], off
	global_load_dwordx2 v[72:73], v[66:67], off offset:16
	global_load_dwordx2 v[70:71], v[66:67], off offset:32
	global_load_dwordx2 v[108:109], v[66:67], off offset:48
	global_load_dwordx2 v[110:111], v[66:67], off offset:64
	s_lshl_b32 s10, s7, 7
	v_max_f32_e32 v75, v149, v149
	s_waitcnt vmcnt(5)
	v_max_f32_e32 v76, v98, v98
	s_lshl_b32 s28, s10, 1
	s_mov_b32 s29, s11
	v_max_f32_e32 v75, v75, v76
	v_lshl_add_u64 v[76:77], v[138:139], 0, s[28:29]
	v_lshl_add_u64 v[104:105], v[76:77], 0, v[140:141]
	v_add_co_u32_e32 v76, vcc, s56, v104
	v_max3_f32 v132, v75, v100, v136
	s_nop 0
	v_addc_co_u32_e32 v77, vcc, 0, v105, vcc
	global_load_dwordx2 v[112:113], v[66:67], off offset:80
	global_load_dwordx2 v[114:115], v[66:67], off offset:96
	global_load_dwordx2 v[116:117], v[66:67], off offset:112
	global_load_dwordx2 v[118:119], v[66:67], off offset:128
	global_load_dwordx2 v[120:121], v[66:67], off offset:144
	global_load_dwordx2 v[122:123], v[66:67], off offset:160
	global_load_dwordx2 v[124:125], v[66:67], off offset:176
	global_load_dwordx2 v[126:127], v[76:77], off offset:2048
	v_sub_f32_e32 v75, v149, v132
	v_sub_f32_e32 v78, v98, v132
	v_exp_f32_e32 v98, v75
	v_exp_f32_e32 v133, v78
	ds_bpermute_b32 v74, v162, v148
	v_ashrrev_i32_e32 v135, 31, v134
	v_pk_mul_f32 v[130:131], v[2:3], v[98:99] op_sel_hi:[1,0]
	v_pk_mul_f32 v[80:81], v[26:27], v[98:99] op_sel_hi:[1,0]
	v_pk_mul_f32 v[84:85], v[22:23], v[98:99] op_sel_hi:[1,0]
	v_pk_mul_f32 v[26:27], v[44:45], v[98:99] op_sel_hi:[1,0]
	v_mul_f32_e32 v44, v99, v133
	v_pk_mul_f32 v[96:97], v[10:11], v[98:99] op_sel_hi:[1,0]
	v_pk_mul_f32 v[94:95], v[12:13], v[98:99] op_sel_hi:[1,0]
	v_pk_mul_f32 v[128:129], v[4:5], v[98:99] op_sel_hi:[1,0]
	v_pk_mul_f32 v[82:83], v[24:25], v[98:99] op_sel_hi:[1,0]
	v_pk_mul_f32 v[92:93], v[14:15], v[98:99] op_sel_hi:[1,0]
	v_pk_mul_f32 v[106:107], v[6:7], v[98:99] op_sel_hi:[1,0]
	v_pk_mul_f32 v[78:79], v[28:29], v[98:99] op_sel_hi:[1,0]
	v_pk_mul_f32 v[90:91], v[16:17], v[98:99] op_sel_hi:[1,0]
	v_pk_mul_f32 v[88:89], v[18:19], v[98:99] op_sel_hi:[1,0]
	s_waitcnt lgkmcnt(0)
	v_add_f32_e32 v138, v148, v74
	v_pk_mul_f32 v[102:103], v[8:9], v[98:99] op_sel_hi:[1,0]
	v_pk_mul_f32 v[74:75], v[32:33], v[98:99] op_sel_hi:[1,0]
	v_pk_mul_f32 v[86:87], v[20:21], v[98:99] op_sel_hi:[1,0]
	v_pk_mul_f32 v[18:19], v[48:49], v[98:99] op_sel_hi:[1,0]
	v_pk_mul_f32 v[48:49], v[34:35], v[98:99] op_sel_hi:[1,0]
	v_pk_mul_f32 v[76:77], v[30:31], v[98:99] op_sel_hi:[1,0]
	v_pk_mul_f32 v[20:21], v[46:47], v[98:99] op_sel_hi:[1,0]
	v_pk_mul_f32 v[46:47], v[36:37], v[98:99] op_sel_hi:[1,0]
	v_pk_mul_f32 v[38:39], v[38:39], v[98:99] op_sel_hi:[1,0]
	v_pk_mul_f32 v[40:41], v[40:41], v[98:99] op_sel_hi:[1,0]
	v_pk_mul_f32 v[30:31], v[42:43], v[98:99] op_sel_hi:[1,0]
	v_pk_mul_f32 v[16:17], v[50:51], v[98:99] op_sel_hi:[1,0]
	v_pk_mul_f32 v[14:15], v[52:53], v[98:99] op_sel_hi:[1,0]
	v_pk_mul_f32 v[12:13], v[54:55], v[98:99] op_sel_hi:[1,0]
	v_pk_mul_f32 v[10:11], v[56:57], v[98:99] op_sel_hi:[1,0]
	v_pk_mul_f32 v[8:9], v[58:59], v[98:99] op_sel_hi:[1,0]
	v_pk_mul_f32 v[6:7], v[60:61], v[98:99] op_sel_hi:[1,0]
	v_pk_mul_f32 v[4:5], v[62:63], v[98:99] op_sel_hi:[1,0]
	v_pk_mul_f32 v[2:3], v[64:65], v[98:99] op_sel_hi:[1,0]
	v_lshlrev_b32_e32 v0, 2, v150
	s_waitcnt vmcnt(12)
	v_lshlrev_b32_e32 v22, 16, v68
	v_fma_f32 v130, v44, v22, v130
	s_waitcnt vmcnt(10)
	v_lshlrev_b32_e32 v22, 16, v70
	v_fma_f32 v96, v44, v22, v96
	v_and_b32_e32 v22, 0xffff0000, v70
	v_and_b32_e32 v23, 0xffff0000, v68
	v_fmac_f32_e32 v97, v44, v22
	v_lshlrev_b32_e32 v22, 16, v71
	v_lshlrev_b32_e32 v24, 16, v69
	v_fmac_f32_e32 v131, v44, v23
	v_fma_f32 v94, v44, v22, v94
	global_load_dwordx2 v[22:23], v[66:67], off offset:192
	v_fma_f32 v128, v44, v24, v128
	v_and_b32_e32 v24, 0xffff0000, v71
	v_fmac_f32_e32 v95, v44, v24
	s_waitcnt vmcnt(10)
	v_lshlrev_b32_e32 v24, 16, v108
	v_and_b32_e32 v25, 0xffff0000, v69
	v_lshlrev_b32_e32 v28, 16, v72
	v_fma_f32 v92, v44, v24, v92
	v_and_b32_e32 v24, 0xffff0000, v108
	v_fmac_f32_e32 v129, v44, v25
	v_fma_f32 v106, v44, v28, v106
	v_fmac_f32_e32 v93, v44, v24
	v_lshlrev_b32_e32 v28, 16, v109
	global_load_dwordx2 v[24:25], v[66:67], off offset:208
	v_fma_f32 v90, v44, v28, v90
	v_and_b32_e32 v28, 0xffff0000, v109
	v_fmac_f32_e32 v91, v44, v28
	s_waitcnt vmcnt(10)
	v_lshlrev_b32_e32 v28, 16, v110
	v_and_b32_e32 v29, 0xffff0000, v72
	v_lshlrev_b32_e32 v32, 16, v73
	v_fma_f32 v88, v44, v28, v88
	v_and_b32_e32 v28, 0xffff0000, v110
	v_fmac_f32_e32 v107, v44, v29
	v_fma_f32 v102, v44, v32, v102
	v_fmac_f32_e32 v89, v44, v28
	global_load_dwordx2 v[28:29], v[66:67], off offset:224
	v_lshlrev_b32_e32 v32, 16, v111
	v_fma_f32 v86, v44, v32, v86
	v_and_b32_e32 v32, 0xffff0000, v111
	v_fmac_f32_e32 v87, v44, v32
	s_waitcnt vmcnt(10)
	v_lshlrev_b32_e32 v32, 16, v112
	v_and_b32_e32 v33, 0xffff0000, v73
	v_fma_f32 v84, v44, v32, v84
	v_and_b32_e32 v32, 0xffff0000, v112
	v_fmac_f32_e32 v103, v44, v33
	v_fmac_f32_e32 v85, v44, v32
	global_load_dwordx2 v[32:33], v[66:67], off offset:240
	v_lshlrev_b32_e32 v34, 16, v113
	v_fma_f32 v82, v44, v34, v82
	v_and_b32_e32 v34, 0xffff0000, v113
	v_fmac_f32_e32 v83, v44, v34
	s_waitcnt vmcnt(10)
	v_lshlrev_b32_e32 v34, 16, v114
	v_fma_f32 v80, v44, v34, v80
	v_and_b32_e32 v34, 0xffff0000, v114
	v_fmac_f32_e32 v81, v44, v34
	v_lshlrev_b32_e32 v34, 16, v115
	v_fma_f32 v78, v44, v34, v78
	v_and_b32_e32 v34, 0xffff0000, v115
	v_fmac_f32_e32 v79, v44, v34
	global_load_dwordx2 v[34:35], v[66:67], off offset:256
	s_waitcnt vmcnt(10)
; __device__ __forceinline__ float bf_lo(unsigned u) { return __uint_as_float(u << 16); }
; __device__ __forceinline__ float bf_hi(unsigned u) { return __uint_as_float(u & 0xffff0000u); }
; __device__ __forceinline__ void moba_own_item(LAS unsigned char* lds, const Ptrs& P, int b, int h, int j) {
;     ...
;     for (int k = 0; k < 3; ++k) if (k < nsel) Mx = fmaxf(Mx, mk[k]);
;     const float wo = __builtin_amdgcn_exp2f(m - Mx); float L = lown * wo;
; #pragma unroll
;     for (int dt = 0; dt < 4; ++dt) o[dt] *= wo;
; #pragma unroll
;     for (int k = 0; k < 3; ++k) if (k < nsel) { const float wk = lk[k] * __builtin_amdgcn_exp2f(mk[k] - Mx); L += wk;
;         const bf16_t* po = P.PO() + (slot0 + k) * 128;
; #pragma unroll
;         for (int dt = 0; dt < 4; ++dt)
; #pragma unroll
;             for (int g4 = 0; g4 < 4; ++g4) { const u32x2 w = *(const u32x2*)(po + 32 * dt + 8 * g4 + 4 * hi);
;                 o[dt][4 * g4] += wk * bf_lo(w.x); o[dt][4 * g4 + 1] += wk * bf_hi(w.x); o[dt][4 * g4 + 2] += wk * bf_lo(w.y); o[dt][4 * g4 + 3] += wk * bf_hi(w.y); } }
	v_lshlrev_b32_e32 v36, 16, v116
	v_fma_f32 v76, v44, v36, v76
	v_and_b32_e32 v36, 0xffff0000, v116
	v_fmac_f32_e32 v77, v44, v36
	v_lshlrev_b32_e32 v36, 16, v117
	v_fma_f32 v74, v44, v36, v74
	v_and_b32_e32 v36, 0xffff0000, v117
	v_fmac_f32_e32 v75, v44, v36
	s_waitcnt vmcnt(9)
	v_lshlrev_b32_e32 v36, 16, v118
	v_fma_f32 v48, v44, v36, v48
	v_and_b32_e32 v36, 0xffff0000, v118
	v_fmac_f32_e32 v49, v44, v36
	v_lshlrev_b32_e32 v36, 16, v119
	v_fma_f32 v140, v44, v36, v46
	v_and_b32_e32 v36, 0xffff0000, v119
	v_fmac_f32_e32 v47, v44, v36
	s_waitcnt vmcnt(8)
	v_lshlrev_b32_e32 v36, 16, v120
	v_fma_f32 v141, v44, v36, v38
	v_and_b32_e32 v36, 0xffff0000, v120
	v_fmac_f32_e32 v39, v44, v36
	v_lshlrev_b32_e32 v36, 16, v121
	v_fma_f32 v142, v44, v36, v40
	v_and_b32_e32 v36, 0xffff0000, v121
	v_fmac_f32_e32 v41, v44, v36
	s_waitcnt vmcnt(7)
	v_lshlrev_b32_e32 v36, 16, v122
	v_fma_f32 v40, v44, v36, v30
	global_load_dwordx2 v[36:37], v[66:67], off offset:512
	v_and_b32_e32 v30, 0xffff0000, v122
	v_fmac_f32_e32 v31, v44, v30
	v_lshlrev_b32_e32 v30, 16, v123
	v_fma_f32 v46, v44, v30, v26
	v_and_b32_e32 v26, 0xffff0000, v123
	v_fmac_f32_e32 v27, v44, v26
	s_waitcnt vmcnt(7)
	v_lshlrev_b32_e32 v26, 16, v124
	v_fma_f32 v30, v44, v26, v20
	v_and_b32_e32 v20, 0xffff0000, v124
	v_fmac_f32_e32 v21, v44, v20
	v_lshlrev_b32_e32 v20, 16, v125
	v_fma_f32 v38, v44, v20, v18
	v_and_b32_e32 v18, 0xffff0000, v125
	v_fmac_f32_e32 v19, v44, v18
	s_waitcnt vmcnt(5)
	v_lshlrev_b32_e32 v18, 16, v22
	v_fma_f32 v20, v44, v18, v16
	v_and_b32_e32 v16, 0xffff0000, v22
	v_fmac_f32_e32 v17, v44, v16
	v_lshlrev_b32_e32 v16, 16, v23
	v_fma_f32 v26, v44, v16, v14
	v_and_b32_e32 v14, 0xffff0000, v23
	v_fmac_f32_e32 v15, v44, v14
	s_waitcnt vmcnt(4)
	v_lshlrev_b32_e32 v14, 16, v24
	v_fma_f32 v16, v44, v14, v12
	v_and_b32_e32 v12, 0xffff0000, v24
	v_fmac_f32_e32 v13, v44, v12
	v_lshlrev_b32_e32 v12, 16, v25
	v_fma_f32 v18, v44, v12, v10
	v_and_b32_e32 v10, 0xffff0000, v25
	v_fmac_f32_e32 v11, v44, v10
	s_waitcnt vmcnt(3)
	v_lshlrev_b32_e32 v10, 16, v28
	v_fma_f32 v8, v44, v10, v8
	v_and_b32_e32 v10, 0xffff0000, v28
	v_fmac_f32_e32 v9, v44, v10
	v_lshlrev_b32_e32 v10, 16, v29
	v_fma_f32 v10, v44, v10, v6
	v_and_b32_e32 v6, 0xffff0000, v29
	v_fmac_f32_e32 v7, v44, v6
	global_load_dwordx2 v[110:111], v[66:67], off offset:272
	global_load_dwordx2 v[112:113], v[66:67], off offset:288
	s_waitcnt vmcnt(4)
	v_lshlrev_b32_e32 v6, 16, v32
	v_fma_f32 v4, v44, v6, v4
	v_and_b32_e32 v6, 0xffff0000, v32
	v_fmac_f32_e32 v5, v44, v6
	v_lshlrev_b32_e32 v6, 16, v33
	v_fma_f32 v2, v44, v6, v2
	v_sub_f32_e32 v6, v100, v132
	v_exp_f32_e32 v12, v6
	v_and_b32_e32 v6, 0xffff0000, v33
	v_fmac_f32_e32 v3, v44, v6
	v_fmac_f32_e32 v44, v138, v98
	v_mul_f32_e32 v6, v101, v12
	v_fmac_f32_e32 v44, v101, v12
	s_waitcnt vmcnt(3)
	v_lshlrev_b32_e32 v14, 16, v34
	v_fmac_f32_e32 v130, v6, v14
	v_and_b32_e32 v14, 0xffff0000, v34
	v_fmac_f32_e32 v131, v6, v14
	v_lshlrev_b32_e32 v14, 16, v35
	v_fmac_f32_e32 v128, v6, v14
	v_and_b32_e32 v14, 0xffff0000, v35
	v_fmac_f32_e32 v129, v6, v14
	v_sub_f32_e32 v14, v136, v132
	v_exp_f32_e32 v14, v14
	v_lshlrev_b32_e32 v35, 16, v126
	global_load_dwordx2 v[114:115], v[66:67], off offset:304
	global_load_dwordx2 v[116:117], v[66:67], off offset:320
	global_load_dwordx2 v[118:119], v[66:67], off offset:336
	global_load_dwordx2 v[108:109], v[66:67], off offset:352
	global_load_dwordx2 v[72:73], v[66:67], off offset:368
	global_load_dwordx2 v[68:69], v[66:67], off offset:384
	global_load_dwordx2 v[62:63], v[66:67], off offset:400
	global_load_dwordx2 v[58:59], v[66:67], off offset:416
	global_load_dwordx2 v[54:55], v[66:67], off offset:432
	global_load_dwordx2 v[50:51], v[66:67], off offset:448
	global_load_dwordx2 v[42:43], v[66:67], off offset:464
	global_load_dwordx2 v[32:33], v[66:67], off offset:480
	v_fmac_f32_e32 v44, v137, v14
	v_mul_f32_e32 v12, v137, v14
	v_rcp_f32_e32 v14, v44
	global_load_dwordx2 v[22:23], v[66:67], off offset:496
	global_load_dwordx2 v[100:101], v[66:67], off offset:528
	global_load_dwordx2 v[120:121], v[66:67], off offset:544
	global_load_dwordx2 v[122:123], v[66:67], off offset:560
	global_load_dwordx2 v[124:125], v[66:67], off offset:576
	global_load_dwordx2 v[132:133], v[66:67], off offset:592
	global_load_dwordx2 v[138:139], v[66:67], off offset:608
	global_load_dwordx2 v[98:99], v[66:67], off offset:624
	global_load_dwordx2 v[70:71], v[66:67], off offset:640
	global_load_dwordx2 v[64:65], v[66:67], off offset:656
	global_load_dwordx2 v[60:61], v[66:67], off offset:672
	v_mul_f32_e32 v14, 0x41800000, v14
	s_waitcnt vmcnt(25)
; __device__ __forceinline__ float bf_lo(unsigned u) { return __uint_as_float(u << 16); }
; __device__ __forceinline__ float bf_hi(unsigned u) { return __uint_as_float(u & 0xffff0000u); }
; __device__ __forceinline__ void moba_own_item(LAS unsigned char* lds, const Ptrs& P, int b, int h, int j) {
;     ...
;     for (int k = 0; k < 3; ++k) if (k < nsel) { const float wk = lk[k] * __builtin_amdgcn_exp2f(mk[k] - Mx); L += wk;
;         const bf16_t* po = P.PO() + (slot0 + k) * 128;
; #pragma unroll
;         for (int dt = 0; dt < 4; ++dt)
; #pragma unroll
;             for (int g4 = 0; g4 < 4; ++g4) { const u32x2 w = *(const u32x2*)(po + 32 * dt + 8 * g4 + 4 * hi);
;                 o[dt][4 * g4] += wk * bf_lo(w.x); o[dt][4 * g4 + 1] += wk * bf_hi(w.x); o[dt][4 * g4 + 2] += wk * bf_lo(w.y); o[dt][4 * g4 + 3] += wk * bf_hi(w.y); } }
;     const float inv = __builtin_amdgcn_rcpf(L);
; #pragma unroll
;     for (int dt = 0; dt < 4; ++dt)
; #pragma unroll
;         for (int g4 = 0; g4 < 4; ++g4) { const int d = 32 * dt + 8 * g4 + 4 * hi;
;             const u32x2 gw = *(const u32x2*)(P.PA() + qrow * NA + C_GA + h * 128 + d);
;             const float i64 = inv * 16.f; int w8 = 0;
;             w8 = __builtin_amdgcn_cvt_pk_fp8_f32(o[dt][4 * g4] * i64 * bf_lo(gw.x), o[dt][4 * g4 + 1] * i64 * bf_hi(gw.x), w8, false); w8 = __builtin_amdgcn_cvt_pk_fp8_f32(o[dt][4 * g4 + 2] * i64 * bf_lo(gw.y), o[dt][4 * g4 + 3] * i64 * bf_hi(gw.y), w8, true);
;             *(unsigned*)(P.Y8() + qrow * 2048 + h * 128 + d) = (unsigned)w8; }
	v_lshlrev_b32_e32 v24, 16, v36
	v_fmac_f32_e32 v130, v12, v24
	v_and_b32_e32 v24, 0xffff0000, v36
	v_fmac_f32_e32 v131, v12, v24
	v_lshlrev_b32_e32 v24, 16, v37
	v_mul_f32_e32 v34, v14, v130
	v_fmac_f32_e32 v128, v12, v24
	v_and_b32_e32 v24, 0xffff0000, v37
	global_load_dwordx2 v[56:57], v[66:67], off offset:688
	global_load_dwordx2 v[52:53], v[66:67], off offset:704
	global_load_dwordx2 v[44:45], v[66:67], off offset:720
	global_load_dwordx2 v[36:37], v[66:67], off offset:736
	global_load_dwordx2 v[28:29], v[66:67], off offset:752
	v_mul_f32_e32 v34, v34, v35
	v_mul_f32_e32 v35, v14, v131
	v_and_b32_e32 v66, 0xffff0000, v126
	v_mul_f32_e32 v35, v35, v66
	v_mov_b32_e32 v66, v1
	v_cvt_pk_fp8_f32 v66, v34, v35
	v_fmac_f32_e32 v129, v12, v24
	v_mul_f32_e32 v34, v14, v128
	v_lshlrev_b32_e32 v35, 16, v127
	v_mul_f32_e32 v34, v34, v35
	v_mul_f32_e32 v35, v14, v129
	v_and_b32_e32 v67, 0xffff0000, v127
	v_mul_f32_e32 v35, v35, v67
	v_lshlrev_b64 v[24:25], 11, v[134:135]
	v_cvt_pk_fp8_f32 v66, v34, v35 op_sel:[0,0,1]
	v_lshl_add_u64 v[24:25], s[24:25], 0, v[24:25]
	v_lshl_add_u64 v[24:25], v[24:25], 0, s[10:11]
	v_lshl_add_u64 v[24:25], v[24:25], 0, v[0:1]
	v_lshl_add_u64 v[34:35], v[104:105], 0, s[26:27]
	global_store_dword v[24:25], v66, off
	global_load_dwordx2 v[66:67], v[34:35], off offset:16
	global_load_dwordx2 v[202:203], v[34:35], off offset:32
	global_load_dwordx2 v[204:205], v[34:35], off offset:48
	global_load_dwordx2 v[206:207], v[34:35], off offset:64
	global_load_dwordx2 v[208:209], v[34:35], off offset:80
	global_load_dwordx2 v[210:211], v[34:35], off offset:96
	global_load_dwordx2 v[212:213], v[34:35], off offset:112
	global_load_dwordx2 v[214:215], v[34:35], off offset:128
	global_load_dwordx2 v[216:217], v[34:35], off offset:144
	global_load_dwordx2 v[218:219], v[34:35], off offset:160
	global_load_dwordx2 v[220:221], v[34:35], off offset:176
	global_load_dwordx2 v[222:223], v[34:35], off offset:192
	global_load_dwordx2 v[224:225], v[34:35], off offset:208
	global_load_dwordx2 v[226:227], v[34:35], off offset:224
	global_load_dwordx2 v[228:229], v[34:35], off offset:240
	s_waitcnt vmcnt(45)
	v_lshlrev_b32_e32 v0, 16, v110
	v_fmac_f32_e32 v106, v6, v0
	v_and_b32_e32 v0, 0xffff0000, v110
	v_fmac_f32_e32 v107, v6, v0
	v_lshlrev_b32_e32 v0, 16, v111
	v_fmac_f32_e32 v102, v6, v0
	v_and_b32_e32 v0, 0xffff0000, v111
	v_fmac_f32_e32 v103, v6, v0
	s_waitcnt vmcnt(30)
	v_lshlrev_b32_e32 v0, 16, v100
	v_fmac_f32_e32 v106, v12, v0
	v_and_b32_e32 v0, 0xffff0000, v100
	v_fmac_f32_e32 v107, v12, v0
	v_lshlrev_b32_e32 v0, 16, v101
	v_fmac_f32_e32 v102, v12, v0
	v_and_b32_e32 v0, 0xffff0000, v101
	v_fmac_f32_e32 v103, v12, v0
	v_mul_f32_e32 v0, v14, v106
	s_waitcnt vmcnt(28)
	v_lshlrev_b32_e32 v101, 16, v123
	s_waitcnt vmcnt(14)
	v_lshlrev_b32_e32 v100, 16, v66
	v_mul_f32_e32 v0, v0, v100
	v_mul_f32_e32 v100, v14, v107
	v_and_b32_e32 v66, 0xffff0000, v66
	v_mul_f32_e32 v66, v100, v66
	v_mov_b32_e32 v100, v1
	v_cvt_pk_fp8_f32 v100, v0, v66
	v_mul_f32_e32 v0, v14, v102
	v_lshlrev_b32_e32 v66, 16, v67
	v_mul_f32_e32 v0, v0, v66
	v_mul_f32_e32 v66, v14, v103
	v_and_b32_e32 v67, 0xffff0000, v67
	v_mul_f32_e32 v66, v66, v67
	v_cvt_pk_fp8_f32 v100, v0, v66 op_sel:[0,0,1]
	v_lshlrev_b32_e32 v0, 16, v112
	v_fmac_f32_e32 v96, v6, v0
	v_and_b32_e32 v0, 0xffff0000, v112
	global_store_dword v[24:25], v100, off offset:8
	s_nop 0
	v_fmac_f32_e32 v97, v6, v0
	v_lshlrev_b32_e32 v0, 16, v113
	v_fmac_f32_e32 v94, v6, v0
	v_and_b32_e32 v0, 0xffff0000, v113
	v_fmac_f32_e32 v95, v6, v0
	v_lshlrev_b32_e32 v0, 16, v120
	v_fmac_f32_e32 v96, v12, v0
	v_and_b32_e32 v0, 0xffff0000, v120
	v_fmac_f32_e32 v97, v12, v0
	v_lshlrev_b32_e32 v0, 16, v121
	v_fmac_f32_e32 v94, v12, v0
	v_and_b32_e32 v0, 0xffff0000, v121
	v_fmac_f32_e32 v95, v12, v0
	v_mul_f32_e32 v0, v14, v96
	v_and_b32_e32 v100, 0xffff0000, v122
	v_and_b32_e32 v102, 0xffff0000, v123
	s_waitcnt vmcnt(14)
	v_lshlrev_b32_e32 v96, 16, v202
	v_mul_f32_e32 v0, v0, v96
	v_mul_f32_e32 v96, v14, v97
	v_and_b32_e32 v66, 0xffff0000, v202
	v_mul_f32_e32 v66, v96, v66
	v_mov_b32_e32 v96, v1
	v_cvt_pk_fp8_f32 v96, v0, v66
	v_mul_f32_e32 v0, v14, v94
	v_lshlrev_b32_e32 v66, 16, v203
	v_mul_f32_e32 v0, v0, v66
	v_mul_f32_e32 v66, v14, v95
	v_and_b32_e32 v67, 0xffff0000, v203
	v_mul_f32_e32 v66, v66, v67
	v_cvt_pk_fp8_f32 v96, v0, v66 op_sel:[0,0,1]
	v_lshlrev_b32_e32 v0, 16, v114
	v_and_b32_e32 v94, 0xffff0000, v114
	v_lshlrev_b32_e32 v97, 16, v122
	global_store_dword v[24:25], v96, off offset:16
	s_nop 0
	v_fmac_f32_e32 v92, v6, v0
	v_fmac_f32_e32 v93, v6, v94
	v_fmac_f32_e32 v92, v12, v97
	v_fmac_f32_e32 v93, v12, v100
	v_mul_f32_e32 v0, v14, v92
	v_lshlrev_b32_e32 v95, 16, v115
	v_and_b32_e32 v96, 0xffff0000, v115
	v_fmac_f32_e32 v90, v6, v95
	v_fmac_f32_e32 v91, v6, v96
	v_fmac_f32_e32 v90, v12, v101
	v_fmac_f32_e32 v91, v12, v102
	v_lshlrev_b32_e32 v94, 16, v124
	v_and_b32_e32 v95, 0xffff0000, v124
	v_lshlrev_b32_e32 v96, 16, v125
	v_and_b32_e32 v97, 0xffff0000, v125
	s_waitcnt vmcnt(14)
	v_lshlrev_b32_e32 v92, 16, v204
	v_mul_f32_e32 v0, v0, v92
	v_mul_f32_e32 v92, v14, v93
	v_and_b32_e32 v66, 0xffff0000, v204
	v_mul_f32_e32 v66, v92, v66
	v_mov_b32_e32 v92, v1
	v_cvt_pk_fp8_f32 v92, v0, v66
	v_mul_f32_e32 v0, v14, v90
	v_lshlrev_b32_e32 v66, 16, v205
	v_mul_f32_e32 v0, v0, v66
	v_mul_f32_e32 v66, v14, v91
	v_and_b32_e32 v67, 0xffff0000, v205
	v_mul_f32_e32 v66, v66, v67
	v_cvt_pk_fp8_f32 v92, v0, v66 op_sel:[0,0,1]
	v_lshlrev_b32_e32 v90, 16, v116
	v_and_b32_e32 v91, 0xffff0000, v116
	v_fmac_f32_e32 v88, v6, v90
	global_store_dword v[24:25], v92, off offset:24
	s_nop 0
	v_fmac_f32_e32 v89, v6, v91
	v_fmac_f32_e32 v88, v12, v94
	v_fmac_f32_e32 v89, v12, v95
	v_mul_f32_e32 v88, v14, v88
	v_mul_f32_e32 v89, v14, v89
	v_mov_b32_e32 v0, v1
	v_lshlrev_b32_e32 v92, 16, v117
	v_and_b32_e32 v93, 0xffff0000, v117
	v_fmac_f32_e32 v86, v6, v92
	v_fmac_f32_e32 v87, v6, v93
	v_fmac_f32_e32 v86, v12, v96
	v_fmac_f32_e32 v87, v12, v97
	v_mul_f32_e32 v86, v14, v86
	v_mul_f32_e32 v87, v14, v87
	v_lshlrev_b32_e32 v92, 16, v133
	v_and_b32_e32 v93, 0xffff0000, v133
	s_waitcnt vmcnt(14)
; __device__ __forceinline__ float bf_lo(unsigned u) { return __uint_as_float(u << 16); }
; __device__ __forceinline__ float bf_hi(unsigned u) { return __uint_as_float(u & 0xffff0000u); }
; __device__ __forceinline__ void moba_own_item(LAS unsigned char* lds, const Ptrs& P, int b, int h, int j) {
;     ...
;     const float inv = __builtin_amdgcn_rcpf(L);
; #pragma unroll
;     for (int dt = 0; dt < 4; ++dt)
; #pragma unroll
;         for (int g4 = 0; g4 < 4; ++g4) { const int d = 32 * dt + 8 * g4 + 4 * hi;
;             const u32x2 gw = *(const u32x2*)(P.PA() + qrow * NA + C_GA + h * 128 + d);
;             const float i64 = inv * 16.f; int w8 = 0;
;             w8 = __builtin_amdgcn_cvt_pk_fp8_f32(o[dt][4 * g4] * i64 * bf_lo(gw.x), o[dt][4 * g4 + 1] * i64 * bf_hi(gw.x), w8, false); w8 = __builtin_amdgcn_cvt_pk_fp8_f32(o[dt][4 * g4 + 2] * i64 * bf_lo(gw.y), o[dt][4 * g4 + 3] * i64 * bf_hi(gw.y), w8, true);
;             *(unsigned*)(P.Y8() + qrow * 2048 + h * 128 + d) = (unsigned)w8; }
	v_lshlrev_b32_e32 v90, 16, v206
	v_and_b32_e32 v66, 0xffff0000, v206
	v_mul_f32_e32 v88, v88, v90
	v_mul_f32_e32 v66, v89, v66
	v_cvt_pk_fp8_f32 v0, v88, v66
	v_lshlrev_b32_e32 v91, 16, v207
	v_and_b32_e32 v66, 0xffff0000, v207
	v_mul_f32_e32 v67, v86, v91
	v_mul_f32_e32 v66, v87, v66
	v_cvt_pk_fp8_f32 v0, v67, v66 op_sel:[0,0,1]
	v_lshlrev_b32_e32 v86, 16, v118
	v_and_b32_e32 v87, 0xffff0000, v118
	v_lshlrev_b32_e32 v90, 16, v132
	global_store_dword v[24:25], v0, off offset:32
	s_nop 0
	v_and_b32_e32 v91, 0xffff0000, v132
	v_fmac_f32_e32 v84, v6, v86
	v_fmac_f32_e32 v85, v6, v87
	v_fmac_f32_e32 v84, v12, v90
	v_fmac_f32_e32 v85, v12, v91
	v_mul_f32_e32 v84, v14, v84
	v_mul_f32_e32 v85, v14, v85
	v_mov_b32_e32 v0, v1
	v_lshlrev_b32_e32 v88, 16, v119
	v_and_b32_e32 v89, 0xffff0000, v119
	v_fmac_f32_e32 v82, v6, v88
	v_fmac_f32_e32 v83, v6, v89
	v_fmac_f32_e32 v82, v12, v92
	v_fmac_f32_e32 v83, v12, v93
	v_mul_f32_e32 v82, v14, v82
	v_mul_f32_e32 v83, v14, v83
	v_lshlrev_b32_e32 v88, 16, v139
	v_and_b32_e32 v89, 0xffff0000, v139
	s_waitcnt vmcnt(14)
	v_lshlrev_b32_e32 v86, 16, v208
	v_and_b32_e32 v66, 0xffff0000, v208
	v_mul_f32_e32 v84, v84, v86
	v_mul_f32_e32 v66, v85, v66
	v_cvt_pk_fp8_f32 v0, v84, v66
	v_lshlrev_b32_e32 v87, 16, v209
	v_and_b32_e32 v66, 0xffff0000, v209
	v_mul_f32_e32 v67, v82, v87
	v_mul_f32_e32 v66, v83, v66
	v_cvt_pk_fp8_f32 v0, v67, v66 op_sel:[0,0,1]
	v_lshlrev_b32_e32 v82, 16, v108
	v_and_b32_e32 v83, 0xffff0000, v108
	v_lshlrev_b32_e32 v86, 16, v138
	global_store_dword v[24:25], v0, off offset:40
	s_nop 0
	v_and_b32_e32 v87, 0xffff0000, v138
	v_fmac_f32_e32 v80, v6, v82
	v_fmac_f32_e32 v81, v6, v83
	v_fmac_f32_e32 v80, v12, v86
	v_fmac_f32_e32 v81, v12, v87
	v_mul_f32_e32 v80, v14, v80
	v_mul_f32_e32 v81, v14, v81
	v_mov_b32_e32 v0, v1
	v_lshlrev_b32_e32 v84, 16, v109
	v_and_b32_e32 v85, 0xffff0000, v109
	v_fmac_f32_e32 v78, v6, v84
	v_fmac_f32_e32 v79, v6, v85
	v_fmac_f32_e32 v78, v12, v88
	v_fmac_f32_e32 v79, v12, v89
	v_mul_f32_e32 v78, v14, v78
	v_mul_f32_e32 v79, v14, v79
	s_waitcnt vmcnt(14)
	v_lshlrev_b32_e32 v82, 16, v210
	v_and_b32_e32 v66, 0xffff0000, v210
	v_mul_f32_e32 v80, v80, v82
	v_mul_f32_e32 v66, v81, v66
	v_cvt_pk_fp8_f32 v0, v80, v66
	v_lshlrev_b32_e32 v83, 16, v211
	v_and_b32_e32 v66, 0xffff0000, v211
	v_mul_f32_e32 v67, v78, v83
	v_mul_f32_e32 v66, v79, v66
	v_cvt_pk_fp8_f32 v0, v67, v66 op_sel:[0,0,1]
	v_lshlrev_b32_e32 v78, 16, v72
	v_and_b32_e32 v72, 0xffff0000, v72
	v_lshlrev_b32_e32 v80, 16, v98
	global_store_dword v[24:25], v0, off offset:48
	s_nop 0
	v_and_b32_e32 v81, 0xffff0000, v98
	v_fmac_f32_e32 v76, v6, v78
	v_fmac_f32_e32 v77, v6, v72
	v_lshlrev_b32_e32 v79, 16, v73
	v_and_b32_e32 v73, 0xffff0000, v73
	v_fmac_f32_e32 v76, v12, v80
	v_fmac_f32_e32 v77, v12, v81
	v_fmac_f32_e32 v75, v6, v73
	v_mul_f32_e32 v72, v14, v76
	v_mul_f32_e32 v73, v14, v77
	v_mov_b32_e32 v0, v1
	v_lshlrev_b32_e32 v82, 16, v99
	v_and_b32_e32 v83, 0xffff0000, v99
	v_fmac_f32_e32 v74, v6, v79
	v_fmac_f32_e32 v74, v12, v82
	v_fmac_f32_e32 v75, v12, v83
	v_mul_f32_e32 v74, v14, v74
	v_mul_f32_e32 v75, v14, v75
	s_waitcnt vmcnt(14)
	v_lshlrev_b32_e32 v76, 16, v212
	v_and_b32_e32 v66, 0xffff0000, v212
	v_mul_f32_e32 v72, v72, v76
	v_mul_f32_e32 v66, v73, v66
	v_cvt_pk_fp8_f32 v0, v72, v66
	v_lshlrev_b32_e32 v77, 16, v213
	v_and_b32_e32 v66, 0xffff0000, v213
	v_mul_f32_e32 v67, v74, v77
	v_mul_f32_e32 v66, v75, v66
	v_cvt_pk_fp8_f32 v0, v67, v66 op_sel:[0,0,1]
	v_lshlrev_b32_e32 v72, 16, v68
	v_and_b32_e32 v68, 0xffff0000, v68
	v_lshlrev_b32_e32 v74, 16, v70
	global_store_dword v[24:25], v0, off offset:56
	s_nop 0
	v_and_b32_e32 v70, 0xffff0000, v70
	v_fmac_f32_e32 v48, v6, v72
	v_fmac_f32_e32 v49, v6, v68
	v_lshlrev_b32_e32 v73, 16, v69
	v_and_b32_e32 v69, 0xffff0000, v69
	v_fmac_f32_e32 v48, v12, v74
	v_fmac_f32_e32 v49, v12, v70
	v_fmac_f32_e32 v47, v6, v69
	v_mul_f32_e32 v48, v14, v48
	v_mul_f32_e32 v49, v14, v49
	v_mov_b32_e32 v0, v1
	v_lshlrev_b32_e32 v75, 16, v71
	v_and_b32_e32 v71, 0xffff0000, v71
	v_fmac_f32_e32 v140, v6, v73
	v_fmac_f32_e32 v140, v12, v75
	v_fmac_f32_e32 v47, v12, v71
	v_mul_f32_e32 v68, v14, v140
	v_mul_f32_e32 v47, v14, v47
	s_waitcnt vmcnt(14)
	v_lshlrev_b32_e32 v69, 16, v214
	v_and_b32_e32 v66, 0xffff0000, v214
	v_mul_f32_e32 v48, v48, v69
	v_mul_f32_e32 v49, v49, v66
	v_cvt_pk_fp8_f32 v0, v48, v49
	v_lshlrev_b32_e32 v70, 16, v215
	v_and_b32_e32 v48, 0xffff0000, v215
	v_mul_f32_e32 v49, v68, v70
	v_mul_f32_e32 v47, v47, v48
	v_cvt_pk_fp8_f32 v0, v49, v47 op_sel:[0,0,1]
	v_lshlrev_b32_e32 v47, 16, v62
	v_and_b32_e32 v62, 0xffff0000, v62
	v_lshlrev_b32_e32 v67, 16, v64
	global_store_dword v[24:25], v0, off offset:64
	s_nop 0
	v_and_b32_e32 v64, 0xffff0000, v64
	v_fmac_f32_e32 v141, v6, v47
	v_fmac_f32_e32 v39, v6, v62
	v_lshlrev_b32_e32 v66, 16, v63
	v_and_b32_e32 v63, 0xffff0000, v63
	v_fmac_f32_e32 v141, v12, v67
	v_fmac_f32_e32 v39, v12, v64
	v_fmac_f32_e32 v41, v6, v63
	v_mul_f32_e32 v47, v14, v141
	v_mul_f32_e32 v39, v14, v39
	v_mov_b32_e32 v0, v1
	v_lshlrev_b32_e32 v68, 16, v65
	v_and_b32_e32 v65, 0xffff0000, v65
	v_fmac_f32_e32 v142, v6, v66
	v_fmac_f32_e32 v142, v12, v68
	v_fmac_f32_e32 v41, v12, v65
	v_mul_f32_e32 v62, v14, v142
	v_mul_f32_e32 v41, v14, v41
	s_waitcnt vmcnt(14)
; __device__ __forceinline__ float bf_lo(unsigned u) { return __uint_as_float(u << 16); }
; __device__ __forceinline__ float bf_hi(unsigned u) { return __uint_as_float(u & 0xffff0000u); }
; __device__ __forceinline__ void moba_own_item(LAS unsigned char* lds, const Ptrs& P, int b, int h, int j) {
;     ...
;     const float inv = __builtin_amdgcn_rcpf(L);
; #pragma unroll
;     for (int dt = 0; dt < 4; ++dt)
; #pragma unroll
;         for (int g4 = 0; g4 < 4; ++g4) { const int d = 32 * dt + 8 * g4 + 4 * hi;
;             const u32x2 gw = *(const u32x2*)(P.PA() + qrow * NA + C_GA + h * 128 + d);
;             const float i64 = inv * 16.f; int w8 = 0;
;             w8 = __builtin_amdgcn_cvt_pk_fp8_f32(o[dt][4 * g4] * i64 * bf_lo(gw.x), o[dt][4 * g4 + 1] * i64 * bf_hi(gw.x), w8, false); w8 = __builtin_amdgcn_cvt_pk_fp8_f32(o[dt][4 * g4 + 2] * i64 * bf_lo(gw.y), o[dt][4 * g4 + 3] * i64 * bf_hi(gw.y), w8, true);
;             *(unsigned*)(P.Y8() + qrow * 2048 + h * 128 + d) = (unsigned)w8; }
;     __syncthreads();
	v_lshlrev_b32_e32 v63, 16, v216
	v_and_b32_e32 v48, 0xffff0000, v216
	v_mul_f32_e32 v47, v47, v63
	v_mul_f32_e32 v39, v39, v48
	v_cvt_pk_fp8_f32 v0, v47, v39
	v_lshlrev_b32_e32 v64, 16, v217
	v_and_b32_e32 v39, 0xffff0000, v217
	v_mul_f32_e32 v47, v62, v64
	v_mul_f32_e32 v39, v41, v39
	v_cvt_pk_fp8_f32 v0, v47, v39 op_sel:[0,0,1]
	v_lshlrev_b32_e32 v39, 16, v58
	v_and_b32_e32 v41, 0xffff0000, v58
	v_lshlrev_b32_e32 v47, 16, v59
	global_store_dword v[24:25], v0, off offset:72
	s_nop 0
	v_and_b32_e32 v58, 0xffff0000, v59
	v_lshlrev_b32_e32 v59, 16, v60
	v_and_b32_e32 v60, 0xffff0000, v60
	v_lshlrev_b32_e32 v62, 16, v61
	v_fmac_f32_e32 v40, v6, v39
	v_fmac_f32_e32 v31, v6, v41
	v_fmac_f32_e32 v46, v6, v47
	v_fmac_f32_e32 v40, v12, v59
	v_fmac_f32_e32 v31, v12, v60
	v_fmac_f32_e32 v46, v12, v62
	v_mul_f32_e32 v39, v14, v40
	v_mul_f32_e32 v31, v14, v31
	v_mul_f32_e32 v40, v14, v46
	v_mov_b32_e32 v0, v1
	v_and_b32_e32 v61, 0xffff0000, v61
	v_fmac_f32_e32 v27, v6, v58
	v_fmac_f32_e32 v27, v12, v61
	v_mul_f32_e32 v27, v14, v27
	s_waitcnt vmcnt(14)
	v_lshlrev_b32_e32 v41, 16, v218
	v_and_b32_e32 v46, 0xffff0000, v218
	v_mul_f32_e32 v39, v39, v41
	v_mul_f32_e32 v31, v31, v46
	v_cvt_pk_fp8_f32 v0, v39, v31
	v_lshlrev_b32_e32 v47, 16, v219
	v_and_b32_e32 v31, 0xffff0000, v219
	v_mul_f32_e32 v39, v40, v47
	v_mul_f32_e32 v27, v27, v31
	v_cvt_pk_fp8_f32 v0, v39, v27 op_sel:[0,0,1]
	v_lshlrev_b32_e32 v27, 16, v54
	v_and_b32_e32 v31, 0xffff0000, v54
	v_lshlrev_b32_e32 v39, 16, v55
	global_store_dword v[24:25], v0, off offset:80
	s_nop 0
	v_lshlrev_b32_e32 v47, 16, v56
	v_and_b32_e32 v48, 0xffff0000, v56
	v_lshlrev_b32_e32 v49, 16, v57
	v_fmac_f32_e32 v30, v6, v27
	v_fmac_f32_e32 v21, v6, v31
	v_fmac_f32_e32 v38, v6, v39
	v_fmac_f32_e32 v30, v12, v47
	v_fmac_f32_e32 v21, v12, v48
	v_fmac_f32_e32 v38, v12, v49
	v_mul_f32_e32 v27, v14, v30
	v_mul_f32_e32 v21, v14, v21
	v_mul_f32_e32 v30, v14, v38
	v_mov_b32_e32 v0, v1
	v_and_b32_e32 v46, 0xffff0000, v55
	v_and_b32_e32 v54, 0xffff0000, v57
	v_fmac_f32_e32 v19, v6, v46
	v_fmac_f32_e32 v19, v12, v54
	v_mul_f32_e32 v19, v14, v19
	v_and_b32_e32 v46, 0xffff0000, v53
	s_waitcnt vmcnt(14)
	v_lshlrev_b32_e32 v31, 16, v220
	v_and_b32_e32 v38, 0xffff0000, v220
	v_mul_f32_e32 v27, v27, v31
	v_mul_f32_e32 v21, v21, v38
	v_cvt_pk_fp8_f32 v0, v27, v21
	v_lshlrev_b32_e32 v39, 16, v221
	v_and_b32_e32 v21, 0xffff0000, v221
	v_mul_f32_e32 v27, v30, v39
	v_mul_f32_e32 v19, v19, v21
	v_cvt_pk_fp8_f32 v0, v27, v19 op_sel:[0,0,1]
	v_lshlrev_b32_e32 v19, 16, v50
	v_and_b32_e32 v21, 0xffff0000, v50
	v_lshlrev_b32_e32 v27, 16, v51
	global_store_dword v[24:25], v0, off offset:88
	s_nop 0
	v_lshlrev_b32_e32 v39, 16, v52
	v_and_b32_e32 v40, 0xffff0000, v52
	v_lshlrev_b32_e32 v41, 16, v53
	v_fmac_f32_e32 v20, v6, v19
	v_fmac_f32_e32 v17, v6, v21
	v_fmac_f32_e32 v26, v6, v27
	v_fmac_f32_e32 v20, v12, v39
	v_fmac_f32_e32 v17, v12, v40
	v_fmac_f32_e32 v26, v12, v41
	v_mul_f32_e32 v19, v14, v20
	v_mul_f32_e32 v17, v14, v17
	v_mul_f32_e32 v20, v14, v26
	v_mov_b32_e32 v0, v1
	v_and_b32_e32 v38, 0xffff0000, v51
	v_fmac_f32_e32 v15, v6, v38
	v_fmac_f32_e32 v15, v12, v46
	v_mul_f32_e32 v15, v14, v15
	v_and_b32_e32 v38, 0xffff0000, v45
	s_waitcnt vmcnt(14)
	v_lshlrev_b32_e32 v21, 16, v222
	v_and_b32_e32 v26, 0xffff0000, v222
	v_mul_f32_e32 v19, v19, v21
	v_mul_f32_e32 v17, v17, v26
	v_cvt_pk_fp8_f32 v0, v19, v17
	v_lshlrev_b32_e32 v27, 16, v223
	v_and_b32_e32 v17, 0xffff0000, v223
	v_mul_f32_e32 v19, v20, v27
	v_mul_f32_e32 v15, v15, v17
	v_cvt_pk_fp8_f32 v0, v19, v15 op_sel:[0,0,1]
	v_lshlrev_b32_e32 v15, 16, v42
	v_and_b32_e32 v17, 0xffff0000, v42
	v_lshlrev_b32_e32 v19, 16, v43
	global_store_dword v[24:25], v0, off offset:96
	s_nop 0
	v_lshlrev_b32_e32 v27, 16, v44
	v_and_b32_e32 v30, 0xffff0000, v44
	v_lshlrev_b32_e32 v31, 16, v45
	v_fmac_f32_e32 v16, v6, v15
	v_fmac_f32_e32 v13, v6, v17
	v_fmac_f32_e32 v18, v6, v19
	v_fmac_f32_e32 v16, v12, v27
	v_fmac_f32_e32 v13, v12, v30
	v_fmac_f32_e32 v18, v12, v31
	v_mul_f32_e32 v15, v14, v16
	v_mul_f32_e32 v13, v14, v13
	v_mul_f32_e32 v16, v14, v18
	v_mov_b32_e32 v0, v1
	v_and_b32_e32 v26, 0xffff0000, v43
	v_fmac_f32_e32 v11, v6, v26
	v_fmac_f32_e32 v11, v12, v38
	v_mul_f32_e32 v11, v14, v11
	v_and_b32_e32 v26, 0xffff0000, v37
	s_waitcnt vmcnt(14)
	v_lshlrev_b32_e32 v17, 16, v224
	v_and_b32_e32 v18, 0xffff0000, v224
	v_mul_f32_e32 v15, v15, v17
	v_mul_f32_e32 v13, v13, v18
	v_cvt_pk_fp8_f32 v0, v15, v13
	v_lshlrev_b32_e32 v19, 16, v225
	v_and_b32_e32 v13, 0xffff0000, v225
	v_mul_f32_e32 v15, v16, v19
	v_mul_f32_e32 v11, v11, v13
	v_cvt_pk_fp8_f32 v0, v15, v11 op_sel:[0,0,1]
	v_lshlrev_b32_e32 v11, 16, v32
	v_and_b32_e32 v13, 0xffff0000, v32
	v_lshlrev_b32_e32 v19, 16, v36
	global_store_dword v[24:25], v0, off offset:104
	s_nop 0
	v_and_b32_e32 v20, 0xffff0000, v36
	v_fmac_f32_e32 v8, v6, v11
	v_fmac_f32_e32 v9, v6, v13
	v_fmac_f32_e32 v8, v12, v19
	v_fmac_f32_e32 v9, v12, v20
	v_mul_f32_e32 v8, v14, v8
	v_mul_f32_e32 v9, v14, v9
	v_mov_b32_e32 v0, v1
	v_lshlrev_b32_e32 v15, 16, v33
	v_and_b32_e32 v18, 0xffff0000, v33
	v_lshlrev_b32_e32 v21, 16, v37
	v_fmac_f32_e32 v10, v6, v15
	v_fmac_f32_e32 v7, v6, v18
	v_fmac_f32_e32 v10, v12, v21
	v_fmac_f32_e32 v7, v12, v26
	v_mul_f32_e32 v10, v14, v10
	v_mul_f32_e32 v7, v14, v7
	v_and_b32_e32 v18, 0xffff0000, v29
	s_waitcnt vmcnt(14)
	v_lshlrev_b32_e32 v11, 16, v226
	v_and_b32_e32 v13, 0xffff0000, v226
	v_mul_f32_e32 v8, v8, v11
	v_mul_f32_e32 v9, v9, v13
	v_cvt_pk_fp8_f32 v0, v8, v9
	v_lshlrev_b32_e32 v15, 16, v227
	v_and_b32_e32 v8, 0xffff0000, v227
	v_mul_f32_e32 v9, v10, v15
	v_mul_f32_e32 v7, v7, v8
	v_cvt_pk_fp8_f32 v0, v9, v7 op_sel:[0,0,1]
	v_lshlrev_b32_e32 v7, 16, v22
	v_and_b32_e32 v10, 0xffff0000, v22
	v_lshlrev_b32_e32 v15, 16, v28
	global_store_dword v[24:25], v0, off offset:112
	s_nop 0
	v_and_b32_e32 v16, 0xffff0000, v28
	v_fmac_f32_e32 v4, v6, v7
	v_fmac_f32_e32 v5, v6, v10
	v_lshlrev_b32_e32 v11, 16, v23
	v_and_b32_e32 v13, 0xffff0000, v23
	v_fmac_f32_e32 v4, v12, v15
	v_fmac_f32_e32 v5, v12, v16
	v_fmac_f32_e32 v2, v6, v11
	v_fmac_f32_e32 v3, v6, v13
	v_mul_f32_e32 v4, v14, v4
	v_mul_f32_e32 v5, v14, v5
	v_mov_b32_e32 v0, v1
	v_lshlrev_b32_e32 v17, 16, v29
	v_fmac_f32_e32 v2, v12, v17
	v_fmac_f32_e32 v3, v12, v18
	v_mul_f32_e32 v2, v14, v2
	v_mul_f32_e32 v3, v14, v3
	s_waitcnt vmcnt(14)
	v_lshlrev_b32_e32 v6, 16, v228
	v_and_b32_e32 v7, 0xffff0000, v228
	v_mul_f32_e32 v4, v4, v6
	v_mul_f32_e32 v5, v5, v7
	v_cvt_pk_fp8_f32 v0, v4, v5
	v_lshlrev_b32_e32 v8, 16, v229
	v_and_b32_e32 v4, 0xffff0000, v229
	v_mul_f32_e32 v2, v2, v8
	v_mul_f32_e32 v3, v3, v4
	v_cvt_pk_fp8_f32 v0, v2, v3 op_sel:[0,0,1]
	v_mov_b32_e32 v3, v163
	global_store_dword v[24:25], v0, off offset:120
	s_barrier
; __device__ __forceinline__ int t5_bucket(int n) {
;     if (n < 16) return n;
;     int b = 16;
;     b += (n >= 19); b += (n >= 21); b += (n >= 24); b += (n >= 27); b += (n >= 31); b += (n >= 35); b += (n >= 40); b += (n >= 46);
;     b += (n >= 52); b += (n >= 59); b += (n >= 67); b += (n >= 77); b += (n >= 87); b += (n >= 99); b += (n >= 113);
;     return b;
; }
; __device__ __forceinline__ void moba_own_item(LAS unsigned char* lds, const Ptrs& P, int b, int h, int j) {
;     ...
;     if (tid < 129) lut[tid] = P.rpe[t5_bucket(tid) * 24 + h] * LOG2E;
	s_nop 0
	v_readfirstlane_b32 s58, v3
	v_cmp_gt_i32_e32 vcc, s35, v3
	s_and_saveexec_b64 s[0:1], vcc
	s_cbranch_execz .LBB0_1021
	v_cmp_lt_i32_e32 vcc, 15, v3
	v_mov_b32_e32 v0, v3
	s_and_saveexec_b64 s[4:5], vcc
	s_cbranch_execz .LBB0_1020
	v_cmp_lt_u32_e32 vcc, 18, v3
	s_nop 1
	v_cndmask_b32_e64 v0, 16, 17, vcc
	v_cmp_lt_u32_e32 vcc, 20, v3
	s_nop 1
	v_cndmask_b32_e64 v2, 0, 1, vcc
	v_cmp_lt_u32_e32 vcc, 23, v3
	s_nop 1
	v_addc_co_u32_e32 v0, vcc, v0, v2, vcc
	v_cmp_lt_u32_e32 vcc, 26, v3
	s_nop 1
	v_cndmask_b32_e64 v2, 0, 1, vcc
	v_cmp_lt_u32_e32 vcc, 30, v3
	s_nop 1
	v_addc_co_u32_e32 v0, vcc, v0, v2, vcc
	v_cmp_lt_u32_e32 vcc, 34, v3
	s_nop 1
	v_cndmask_b32_e64 v2, 0, 1, vcc
	v_cmp_lt_u32_e32 vcc, 39, v3
	s_nop 1
	v_addc_co_u32_e32 v0, vcc, v0, v2, vcc
	v_cmp_lt_u32_e32 vcc, 45, v3
	s_nop 1
	v_cndmask_b32_e64 v2, 0, 1, vcc
	v_cmp_lt_u32_e32 vcc, 51, v3
	s_nop 1
	v_addc_co_u32_e32 v0, vcc, v0, v2, vcc
	v_cmp_lt_u32_e32 vcc, 58, v3
	s_nop 1
	v_cndmask_b32_e64 v2, 0, 1, vcc
	v_cmp_lt_u32_e32 vcc, s36, v3
	s_nop 1
	v_addc_co_u32_e32 v0, vcc, v0, v2, vcc
	v_cmp_lt_u32_e32 vcc, s37, v3
	s_nop 1
	v_cndmask_b32_e64 v2, 0, 1, vcc
	v_cmp_lt_u32_e32 vcc, s38, v3
	s_nop 1
	v_addc_co_u32_e32 v0, vcc, v0, v2, vcc
	v_cmp_lt_u32_e32 vcc, s39, v3
	s_nop 1
	v_cndmask_b32_e64 v2, 0, 1, vcc
	v_cmp_lt_u32_e32 vcc, s40, v3
	s_nop 1
	v_addc_co_u32_e32 v0, vcc, v0, v2, vcc

; __device__ __forceinline__ float bf_lo(unsigned u) { return __uint_as_float(u << 16); }
; __device__ __forceinline__ float bf_hi(unsigned u) { return __uint_as_float(u & 0xffff0000u); }
; __device__ __forceinline__ void moba_own_item(LAS unsigned char* lds, const Ptrs& P, int b, int h, int j) {
;     ...
;     float lown = l + __shfl_xor(l, 32);
;     float Mx = m;
; #pragma unroll
;     for (int k = 0; k < 3; ++k) if (k < nsel) Mx = fmaxf(Mx, mk[k]);
;     const float wo = __builtin_amdgcn_exp2f(m - Mx); float L = lown * wo;
; #pragma unroll
;     for (int dt = 0; dt < 4; ++dt) o[dt] *= wo;
; #pragma unroll
;     for (int k = 0; k < 3; ++k) if (k < nsel) { const float wk = lk[k] * __builtin_amdgcn_exp2f(mk[k] - Mx); L += wk;
;         const bf16_t* po = P.PO() + (slot0 + k) * 128;
; #pragma unroll
;         for (int dt = 0; dt < 4; ++dt)
; #pragma unroll
;             for (int g4 = 0; g4 < 4; ++g4) { const u32x2 w = *(const u32x2*)(po + 32 * dt + 8 * g4 + 4 * hi);
;                 o[dt][4 * g4] += wk * bf_lo(w.x); o[dt][4 * g4 + 1] += wk * bf_hi(w.x); o[dt][4 * g4 + 2] += wk * bf_lo(w.y); o[dt][4 * g4 + 3] += wk * bf_hi(w.y); } }
.LBB0_1869:
	v_mov_b32_e32 v141, v1
	v_lshl_add_u64 v[66:67], s[22:23], 0, v[140:141]
	v_mad_u64_u32 v[66:67], s[0:1], v142, s55, v[66:67]
	v_mad_i32_i24 v67, v143, s55, v67
	global_load_dwordx2 v[68:69], v[66:67], off
	global_load_dwordx2 v[72:73], v[66:67], off offset:16
	global_load_dwordx2 v[70:71], v[66:67], off offset:32
	global_load_dwordx2 v[108:109], v[66:67], off offset:48
	global_load_dwordx2 v[110:111], v[66:67], off offset:64
	s_lshl_b32 s10, s7, 7
	v_max_f32_e32 v75, v149, v149
	s_waitcnt vmcnt(5)
	v_max_f32_e32 v76, v98, v98
	s_lshl_b32 s28, s10, 1
	s_mov_b32 s29, s11
	v_max_f32_e32 v75, v75, v76
	v_lshl_add_u64 v[76:77], v[138:139], 0, s[28:29]
	v_lshl_add_u64 v[104:105], v[76:77], 0, v[140:141]
	v_add_co_u32_e32 v76, vcc, s56, v104
	v_max3_f32 v132, v75, v100, v136
	s_nop 0
	v_addc_co_u32_e32 v77, vcc, 0, v105, vcc
	global_load_dwordx2 v[112:113], v[66:67], off offset:80
	global_load_dwordx2 v[114:115], v[66:67], off offset:96
	global_load_dwordx2 v[116:117], v[66:67], off offset:112
	global_load_dwordx2 v[118:119], v[66:67], off offset:128
	global_load_dwordx2 v[120:121], v[66:67], off offset:144
	global_load_dwordx2 v[122:123], v[66:67], off offset:160
	global_load_dwordx2 v[124:125], v[66:67], off offset:176
	global_load_dwordx2 v[126:127], v[76:77], off offset:2048
	v_sub_f32_e32 v75, v149, v132
	v_sub_f32_e32 v78, v98, v132
	v_exp_f32_e32 v98, v75
	v_exp_f32_e32 v133, v78
	ds_bpermute_b32 v74, v162, v148
	v_ashrrev_i32_e32 v135, 31, v134
	v_pk_mul_f32 v[130:131], v[2:3], v[98:99] op_sel_hi:[1,0]
	v_pk_mul_f32 v[80:81], v[26:27], v[98:99] op_sel_hi:[1,0]
	v_pk_mul_f32 v[84:85], v[22:23], v[98:99] op_sel_hi:[1,0]
	v_pk_mul_f32 v[26:27], v[44:45], v[98:99] op_sel_hi:[1,0]
	v_mul_f32_e32 v44, v99, v133
	v_pk_mul_f32 v[96:97], v[10:11], v[98:99] op_sel_hi:[1,0]
	v_pk_mul_f32 v[94:95], v[12:13], v[98:99] op_sel_hi:[1,0]
	v_pk_mul_f32 v[128:129], v[4:5], v[98:99] op_sel_hi:[1,0]
	v_pk_mul_f32 v[82:83], v[24:25], v[98:99] op_sel_hi:[1,0]
	v_pk_mul_f32 v[92:93], v[14:15], v[98:99] op_sel_hi:[1,0]
	v_pk_mul_f32 v[106:107], v[6:7], v[98:99] op_sel_hi:[1,0]
	v_pk_mul_f32 v[78:79], v[28:29], v[98:99] op_sel_hi:[1,0]
	v_pk_mul_f32 v[90:91], v[16:17], v[98:99] op_sel_hi:[1,0]
	v_pk_mul_f32 v[88:89], v[18:19], v[98:99] op_sel_hi:[1,0]
	s_waitcnt lgkmcnt(0)
	v_add_f32_e32 v138, v148, v74
	v_pk_mul_f32 v[102:103], v[8:9], v[98:99] op_sel_hi:[1,0]
	v_pk_mul_f32 v[74:75], v[32:33], v[98:99] op_sel_hi:[1,0]
	v_pk_mul_f32 v[86:87], v[20:21], v[98:99] op_sel_hi:[1,0]
	v_pk_mul_f32 v[18:19], v[48:49], v[98:99] op_sel_hi:[1,0]
	v_pk_mul_f32 v[48:49], v[34:35], v[98:99] op_sel_hi:[1,0]
	v_pk_mul_f32 v[76:77], v[30:31], v[98:99] op_sel_hi:[1,0]
	v_pk_mul_f32 v[20:21], v[46:47], v[98:99] op_sel_hi:[1,0]
	v_pk_mul_f32 v[46:47], v[36:37], v[98:99] op_sel_hi:[1,0]
	v_pk_mul_f32 v[38:39], v[38:39], v[98:99] op_sel_hi:[1,0]
	v_pk_mul_f32 v[40:41], v[40:41], v[98:99] op_sel_hi:[1,0]
	v_pk_mul_f32 v[30:31], v[42:43], v[98:99] op_sel_hi:[1,0]
	v_pk_mul_f32 v[16:17], v[50:51], v[98:99] op_sel_hi:[1,0]
	v_pk_mul_f32 v[14:15], v[52:53], v[98:99] op_sel_hi:[1,0]
	v_pk_mul_f32 v[12:13], v[54:55], v[98:99] op_sel_hi:[1,0]
	v_pk_mul_f32 v[10:11], v[56:57], v[98:99] op_sel_hi:[1,0]
	v_pk_mul_f32 v[8:9], v[58:59], v[98:99] op_sel_hi:[1,0]
	v_pk_mul_f32 v[6:7], v[60:61], v[98:99] op_sel_hi:[1,0]
	v_pk_mul_f32 v[4:5], v[62:63], v[98:99] op_sel_hi:[1,0]
	v_pk_mul_f32 v[2:3], v[64:65], v[98:99] op_sel_hi:[1,0]
	v_lshlrev_b32_e32 v0, 2, v150
	s_waitcnt vmcnt(12)
	v_lshlrev_b32_e32 v22, 16, v68
	v_fma_f32 v130, v44, v22, v130
	s_waitcnt vmcnt(10)
	v_lshlrev_b32_e32 v22, 16, v70
	v_fma_f32 v96, v44, v22, v96
	v_and_b32_e32 v22, 0xffff0000, v70
	v_and_b32_e32 v23, 0xffff0000, v68
	v_fmac_f32_e32 v97, v44, v22
	v_lshlrev_b32_e32 v22, 16, v71
	v_lshlrev_b32_e32 v24, 16, v69
	v_fmac_f32_e32 v131, v44, v23
	v_fma_f32 v94, v44, v22, v94
	global_load_dwordx2 v[22:23], v[66:67], off offset:192
	v_fma_f32 v128, v44, v24, v128
	v_and_b32_e32 v24, 0xffff0000, v71
	v_fmac_f32_e32 v95, v44, v24
	s_waitcnt vmcnt(10)
	v_lshlrev_b32_e32 v24, 16, v108
	v_and_b32_e32 v25, 0xffff0000, v69
	v_lshlrev_b32_e32 v28, 16, v72
	v_fma_f32 v92, v44, v24, v92
	v_and_b32_e32 v24, 0xffff0000, v108
	v_fmac_f32_e32 v129, v44, v25
	v_fma_f32 v106, v44, v28, v106
	v_fmac_f32_e32 v93, v44, v24
	v_lshlrev_b32_e32 v28, 16, v109
	global_load_dwordx2 v[24:25], v[66:67], off offset:208
	v_fma_f32 v90, v44, v28, v90
	v_and_b32_e32 v28, 0xffff0000, v109
	v_fmac_f32_e32 v91, v44, v28
	s_waitcnt vmcnt(10)
	v_lshlrev_b32_e32 v28, 16, v110
	v_and_b32_e32 v29, 0xffff0000, v72
	v_lshlrev_b32_e32 v32, 16, v73
	v_fma_f32 v88, v44, v28, v88
	v_and_b32_e32 v28, 0xffff0000, v110
	v_fmac_f32_e32 v107, v44, v29
	v_fma_f32 v102, v44, v32, v102
	v_fmac_f32_e32 v89, v44, v28
	global_load_dwordx2 v[28:29], v[66:67], off offset:224
	v_lshlrev_b32_e32 v32, 16, v111
	v_fma_f32 v86, v44, v32, v86
	v_and_b32_e32 v32, 0xffff0000, v111
	v_fmac_f32_e32 v87, v44, v32
	s_waitcnt vmcnt(10)
	v_lshlrev_b32_e32 v32, 16, v112
	v_and_b32_e32 v33, 0xffff0000, v73
	v_fma_f32 v84, v44, v32, v84
	v_and_b32_e32 v32, 0xffff0000, v112
	v_fmac_f32_e32 v103, v44, v33
	v_fmac_f32_e32 v85, v44, v32
	global_load_dwordx2 v[32:33], v[66:67], off offset:240
	v_lshlrev_b32_e32 v34, 16, v113
	v_fma_f32 v82, v44, v34, v82
	v_and_b32_e32 v34, 0xffff0000, v113
	v_fmac_f32_e32 v83, v44, v34
	s_waitcnt vmcnt(10)
	v_lshlrev_b32_e32 v34, 16, v114
	v_fma_f32 v80, v44, v34, v80
	v_and_b32_e32 v34, 0xffff0000, v114
	v_fmac_f32_e32 v81, v44, v34
	v_lshlrev_b32_e32 v34, 16, v115
	v_fma_f32 v78, v44, v34, v78
	v_and_b32_e32 v34, 0xffff0000, v115
	v_fmac_f32_e32 v79, v44, v34
	global_load_dwordx2 v[34:35], v[66:67], off offset:256
	s_waitcnt vmcnt(10)
; __device__ __forceinline__ float bf_lo(unsigned u) { return __uint_as_float(u << 16); }
; __device__ __forceinline__ float bf_hi(unsigned u) { return __uint_as_float(u & 0xffff0000u); }
; __device__ __forceinline__ void moba_own_item(LAS unsigned char* lds, const Ptrs& P, int b, int h, int j) {
;     ...
;     for (int k = 0; k < 3; ++k) if (k < nsel) Mx = fmaxf(Mx, mk[k]);
;     const float wo = __builtin_amdgcn_exp2f(m - Mx); float L = lown * wo;
; #pragma unroll
;     for (int dt = 0; dt < 4; ++dt) o[dt] *= wo;
; #pragma unroll
;     for (int k = 0; k < 3; ++k) if (k < nsel) { const float wk = lk[k] * __builtin_amdgcn_exp2f(mk[k] - Mx); L += wk;
;         const bf16_t* po = P.PO() + (slot0 + k) * 128;
; #pragma unroll
;         for (int dt = 0; dt < 4; ++dt)
; #pragma unroll
;             for (int g4 = 0; g4 < 4; ++g4) { const u32x2 w = *(const u32x2*)(po + 32 * dt + 8 * g4 + 4 * hi);
;                 o[dt][4 * g4] += wk * bf_lo(w.x); o[dt][4 * g4 + 1] += wk * bf_hi(w.x); o[dt][4 * g4 + 2] += wk * bf_lo(w.y); o[dt][4 * g4 + 3] += wk * bf_hi(w.y); } }
	v_lshlrev_b32_e32 v36, 16, v116
	v_fma_f32 v76, v44, v36, v76
	v_and_b32_e32 v36, 0xffff0000, v116
	v_fmac_f32_e32 v77, v44, v36
	v_lshlrev_b32_e32 v36, 16, v117
	v_fma_f32 v74, v44, v36, v74
	v_and_b32_e32 v36, 0xffff0000, v117
	v_fmac_f32_e32 v75, v44, v36
	s_waitcnt vmcnt(9)
	v_lshlrev_b32_e32 v36, 16, v118
	v_fma_f32 v48, v44, v36, v48
	v_and_b32_e32 v36, 0xffff0000, v118
	v_fmac_f32_e32 v49, v44, v36
	v_lshlrev_b32_e32 v36, 16, v119
	v_fma_f32 v140, v44, v36, v46
	v_and_b32_e32 v36, 0xffff0000, v119
	v_fmac_f32_e32 v47, v44, v36
	s_waitcnt vmcnt(8)
	v_lshlrev_b32_e32 v36, 16, v120
	v_fma_f32 v141, v44, v36, v38
	v_and_b32_e32 v36, 0xffff0000, v120
	v_fmac_f32_e32 v39, v44, v36
	v_lshlrev_b32_e32 v36, 16, v121
	v_fma_f32 v142, v44, v36, v40
	v_and_b32_e32 v36, 0xffff0000, v121
	v_fmac_f32_e32 v41, v44, v36
	s_waitcnt vmcnt(7)
	v_lshlrev_b32_e32 v36, 16, v122
	v_fma_f32 v40, v44, v36, v30
	global_load_dwordx2 v[36:37], v[66:67], off offset:512
	v_and_b32_e32 v30, 0xffff0000, v122
	v_fmac_f32_e32 v31, v44, v30
	v_lshlrev_b32_e32 v30, 16, v123
	v_fma_f32 v46, v44, v30, v26
	v_and_b32_e32 v26, 0xffff0000, v123
	v_fmac_f32_e32 v27, v44, v26
	s_waitcnt vmcnt(7)
	v_lshlrev_b32_e32 v26, 16, v124
	v_fma_f32 v30, v44, v26, v20
	v_and_b32_e32 v20, 0xffff0000, v124
	v_fmac_f32_e32 v21, v44, v20
	v_lshlrev_b32_e32 v20, 16, v125
	v_fma_f32 v38, v44, v20, v18
	v_and_b32_e32 v18, 0xffff0000, v125
	v_fmac_f32_e32 v19, v44, v18
	s_waitcnt vmcnt(5)
	v_lshlrev_b32_e32 v18, 16, v22
	v_fma_f32 v20, v44, v18, v16
	v_and_b32_e32 v16, 0xffff0000, v22
	v_fmac_f32_e32 v17, v44, v16
	v_lshlrev_b32_e32 v16, 16, v23
	v_fma_f32 v26, v44, v16, v14
	v_and_b32_e32 v14, 0xffff0000, v23
	v_fmac_f32_e32 v15, v44, v14
	s_waitcnt vmcnt(4)
	v_lshlrev_b32_e32 v14, 16, v24
	v_fma_f32 v16, v44, v14, v12
	v_and_b32_e32 v12, 0xffff0000, v24
	v_fmac_f32_e32 v13, v44, v12
	v_lshlrev_b32_e32 v12, 16, v25
	v_fma_f32 v18, v44, v12, v10
	v_and_b32_e32 v10, 0xffff0000, v25
	v_fmac_f32_e32 v11, v44, v10
	s_waitcnt vmcnt(3)
	v_lshlrev_b32_e32 v10, 16, v28
	v_fma_f32 v8, v44, v10, v8
	v_and_b32_e32 v10, 0xffff0000, v28
	v_fmac_f32_e32 v9, v44, v10
	v_lshlrev_b32_e32 v10, 16, v29
	v_fma_f32 v10, v44, v10, v6
	v_and_b32_e32 v6, 0xffff0000, v29
	v_fmac_f32_e32 v7, v44, v6
	global_load_dwordx2 v[110:111], v[66:67], off offset:272
	global_load_dwordx2 v[112:113], v[66:67], off offset:288
	s_waitcnt vmcnt(4)
	v_lshlrev_b32_e32 v6, 16, v32
	v_fma_f32 v4, v44, v6, v4
	v_and_b32_e32 v6, 0xffff0000, v32
	v_fmac_f32_e32 v5, v44, v6
	v_lshlrev_b32_e32 v6, 16, v33
	v_fma_f32 v2, v44, v6, v2
	v_sub_f32_e32 v6, v100, v132
	v_exp_f32_e32 v12, v6
	v_and_b32_e32 v6, 0xffff0000, v33
	v_fmac_f32_e32 v3, v44, v6
	v_fmac_f32_e32 v44, v138, v98
	v_mul_f32_e32 v6, v101, v12
	v_fmac_f32_e32 v44, v101, v12
	s_waitcnt vmcnt(3)
	v_lshlrev_b32_e32 v14, 16, v34
	v_fmac_f32_e32 v130, v6, v14
	v_and_b32_e32 v14, 0xffff0000, v34
	v_fmac_f32_e32 v131, v6, v14
	v_lshlrev_b32_e32 v14, 16, v35
	v_fmac_f32_e32 v128, v6, v14
	v_and_b32_e32 v14, 0xffff0000, v35
	v_fmac_f32_e32 v129, v6, v14
	v_sub_f32_e32 v14, v136, v132
	v_exp_f32_e32 v14, v14
	v_lshlrev_b32_e32 v35, 16, v126
	global_load_dwordx2 v[114:115], v[66:67], off offset:304
	global_load_dwordx2 v[116:117], v[66:67], off offset:320
	global_load_dwordx2 v[118:119], v[66:67], off offset:336
	global_load_dwordx2 v[108:109], v[66:67], off offset:352
	global_load_dwordx2 v[72:73], v[66:67], off offset:368
	global_load_dwordx2 v[68:69], v[66:67], off offset:384
	global_load_dwordx2 v[62:63], v[66:67], off offset:400
	global_load_dwordx2 v[58:59], v[66:67], off offset:416
	global_load_dwordx2 v[54:55], v[66:67], off offset:432
	global_load_dwordx2 v[50:51], v[66:67], off offset:448
	global_load_dwordx2 v[42:43], v[66:67], off offset:464
	global_load_dwordx2 v[32:33], v[66:67], off offset:480
	v_fmac_f32_e32 v44, v137, v14
	v_mul_f32_e32 v12, v137, v14
	v_rcp_f32_e32 v14, v44
	global_load_dwordx2 v[22:23], v[66:67], off offset:496
	global_load_dwordx2 v[100:101], v[66:67], off offset:528
	global_load_dwordx2 v[120:121], v[66:67], off offset:544
	global_load_dwordx2 v[122:123], v[66:67], off offset:560
	global_load_dwordx2 v[124:125], v[66:67], off offset:576
	global_load_dwordx2 v[132:133], v[66:67], off offset:592
	global_load_dwordx2 v[138:139], v[66:67], off offset:608
	global_load_dwordx2 v[98:99], v[66:67], off offset:624
	global_load_dwordx2 v[70:71], v[66:67], off offset:640
	global_load_dwordx2 v[64:65], v[66:67], off offset:656
	global_load_dwordx2 v[60:61], v[66:67], off offset:672
	v_mul_f32_e32 v14, 0x41800000, v14
	s_waitcnt vmcnt(25)
; __device__ __forceinline__ float bf_lo(unsigned u) { return __uint_as_float(u << 16); }
; __device__ __forceinline__ float bf_hi(unsigned u) { return __uint_as_float(u & 0xffff0000u); }
; __device__ __forceinline__ void moba_own_item(LAS unsigned char* lds, const Ptrs& P, int b, int h, int j) {
;     ...
;     for (int k = 0; k < 3; ++k) if (k < nsel) { const float wk = lk[k] * __builtin_amdgcn_exp2f(mk[k] - Mx); L += wk;
;         const bf16_t* po = P.PO() + (slot0 + k) * 128;
; #pragma unroll
;         for (int dt = 0; dt < 4; ++dt)
; #pragma unroll
;             for (int g4 = 0; g4 < 4; ++g4) { const u32x2 w = *(const u32x2*)(po + 32 * dt + 8 * g4 + 4 * hi);
;                 o[dt][4 * g4] += wk * bf_lo(w.x); o[dt][4 * g4 + 1] += wk * bf_hi(w.x); o[dt][4 * g4 + 2] += wk * bf_lo(w.y); o[dt][4 * g4 + 3] += wk * bf_hi(w.y); } }
;     const float inv = __builtin_amdgcn_rcpf(L);
; #pragma unroll
;     for (int dt = 0; dt < 4; ++dt)
; #pragma unroll
;         for (int g4 = 0; g4 < 4; ++g4) { const int d = 32 * dt + 8 * g4 + 4 * hi;
;             const u32x2 gw = *(const u32x2*)(P.PA() + qrow * NA + C_GA + h * 128 + d);
;             const float i64 = inv * 16.f; int w8 = 0;
;             w8 = __builtin_amdgcn_cvt_pk_fp8_f32(o[dt][4 * g4] * i64 * bf_lo(gw.x), o[dt][4 * g4 + 1] * i64 * bf_hi(gw.x), w8, false); w8 = __builtin_amdgcn_cvt_pk_fp8_f32(o[dt][4 * g4 + 2] * i64 * bf_lo(gw.y), o[dt][4 * g4 + 3] * i64 * bf_hi(gw.y), w8, true);
;             *(unsigned*)(P.Y8() + qrow * 2048 + h * 128 + d) = (unsigned)w8; }
	v_lshlrev_b32_e32 v24, 16, v36
	v_fmac_f32_e32 v130, v12, v24
	v_and_b32_e32 v24, 0xffff0000, v36
	v_fmac_f32_e32 v131, v12, v24
	v_lshlrev_b32_e32 v24, 16, v37
	v_mul_f32_e32 v34, v14, v130
	v_fmac_f32_e32 v128, v12, v24
	v_and_b32_e32 v24, 0xffff0000, v37
	global_load_dwordx2 v[56:57], v[66:67], off offset:688
	global_load_dwordx2 v[52:53], v[66:67], off offset:704
	global_load_dwordx2 v[44:45], v[66:67], off offset:720
	global_load_dwordx2 v[36:37], v[66:67], off offset:736
	global_load_dwordx2 v[28:29], v[66:67], off offset:752
	v_mul_f32_e32 v34, v34, v35
	v_mul_f32_e32 v35, v14, v131
	v_and_b32_e32 v66, 0xffff0000, v126
	v_mul_f32_e32 v35, v35, v66
	v_mov_b32_e32 v66, v1
	v_cvt_pk_fp8_f32 v66, v34, v35
	v_fmac_f32_e32 v129, v12, v24
	v_mul_f32_e32 v34, v14, v128
	v_lshlrev_b32_e32 v35, 16, v127
	v_mul_f32_e32 v34, v34, v35
	v_mul_f32_e32 v35, v14, v129
	v_and_b32_e32 v67, 0xffff0000, v127
	v_mul_f32_e32 v35, v35, v67
	v_lshlrev_b64 v[24:25], 11, v[134:135]
	v_cvt_pk_fp8_f32 v66, v34, v35 op_sel:[0,0,1]
	v_lshl_add_u64 v[24:25], s[24:25], 0, v[24:25]
	v_lshl_add_u64 v[24:25], v[24:25], 0, s[10:11]
	v_lshl_add_u64 v[24:25], v[24:25], 0, v[0:1]
	v_lshl_add_u64 v[34:35], v[104:105], 0, s[26:27]
	global_store_dword v[24:25], v66, off
	global_load_dwordx2 v[66:67], v[34:35], off offset:16
	global_load_dwordx2 v[166:167], v[34:35], off offset:32
	global_load_dwordx2 v[168:169], v[34:35], off offset:48
	global_load_dwordx2 v[170:171], v[34:35], off offset:64
	global_load_dwordx2 v[172:173], v[34:35], off offset:80
	global_load_dwordx2 v[174:175], v[34:35], off offset:96
	global_load_dwordx2 v[176:177], v[34:35], off offset:112
	global_load_dwordx2 v[178:179], v[34:35], off offset:128
	global_load_dwordx2 v[180:181], v[34:35], off offset:144
	global_load_dwordx2 v[182:183], v[34:35], off offset:160
	global_load_dwordx2 v[184:185], v[34:35], off offset:176
	global_load_dwordx2 v[186:187], v[34:35], off offset:192
	global_load_dwordx2 v[188:189], v[34:35], off offset:208
	global_load_dwordx2 v[190:191], v[34:35], off offset:224
	global_load_dwordx2 v[192:193], v[34:35], off offset:240
	s_waitcnt vmcnt(45)
	v_lshlrev_b32_e32 v0, 16, v110
	v_fmac_f32_e32 v106, v6, v0
	v_and_b32_e32 v0, 0xffff0000, v110
	v_fmac_f32_e32 v107, v6, v0
	v_lshlrev_b32_e32 v0, 16, v111
	v_fmac_f32_e32 v102, v6, v0
	v_and_b32_e32 v0, 0xffff0000, v111
	v_fmac_f32_e32 v103, v6, v0
	s_waitcnt vmcnt(30)
	v_lshlrev_b32_e32 v0, 16, v100
	v_fmac_f32_e32 v106, v12, v0
	v_and_b32_e32 v0, 0xffff0000, v100
	v_fmac_f32_e32 v107, v12, v0
	v_lshlrev_b32_e32 v0, 16, v101
	v_fmac_f32_e32 v102, v12, v0
	v_and_b32_e32 v0, 0xffff0000, v101
	v_fmac_f32_e32 v103, v12, v0
	v_mul_f32_e32 v0, v14, v106
	s_waitcnt vmcnt(28)
	v_lshlrev_b32_e32 v101, 16, v123
	s_waitcnt vmcnt(14)
	v_lshlrev_b32_e32 v100, 16, v66
	v_mul_f32_e32 v0, v0, v100
	v_mul_f32_e32 v100, v14, v107
	v_and_b32_e32 v66, 0xffff0000, v66
	v_mul_f32_e32 v66, v100, v66
	v_mov_b32_e32 v100, v1
	v_cvt_pk_fp8_f32 v100, v0, v66
	v_mul_f32_e32 v0, v14, v102
	v_lshlrev_b32_e32 v66, 16, v67
	v_mul_f32_e32 v0, v0, v66
	v_mul_f32_e32 v66, v14, v103
	v_and_b32_e32 v67, 0xffff0000, v67
	v_mul_f32_e32 v66, v66, v67
	v_cvt_pk_fp8_f32 v100, v0, v66 op_sel:[0,0,1]
	v_lshlrev_b32_e32 v0, 16, v112
	v_fmac_f32_e32 v96, v6, v0
	v_and_b32_e32 v0, 0xffff0000, v112
	global_store_dword v[24:25], v100, off offset:8
	s_nop 0
	v_fmac_f32_e32 v97, v6, v0
	v_lshlrev_b32_e32 v0, 16, v113
	v_fmac_f32_e32 v94, v6, v0
	v_and_b32_e32 v0, 0xffff0000, v113
	v_fmac_f32_e32 v95, v6, v0
	v_lshlrev_b32_e32 v0, 16, v120
	v_fmac_f32_e32 v96, v12, v0
	v_and_b32_e32 v0, 0xffff0000, v120
	v_fmac_f32_e32 v97, v12, v0
	v_lshlrev_b32_e32 v0, 16, v121
	v_fmac_f32_e32 v94, v12, v0
	v_and_b32_e32 v0, 0xffff0000, v121
	v_fmac_f32_e32 v95, v12, v0
	v_mul_f32_e32 v0, v14, v96
	v_and_b32_e32 v100, 0xffff0000, v122
	v_and_b32_e32 v102, 0xffff0000, v123
	s_waitcnt vmcnt(14)
	v_lshlrev_b32_e32 v96, 16, v166
	v_mul_f32_e32 v0, v0, v96
	v_mul_f32_e32 v96, v14, v97
	v_and_b32_e32 v66, 0xffff0000, v166
	v_mul_f32_e32 v66, v96, v66
	v_mov_b32_e32 v96, v1
	v_cvt_pk_fp8_f32 v96, v0, v66
	v_mul_f32_e32 v0, v14, v94
	v_lshlrev_b32_e32 v66, 16, v167
	v_mul_f32_e32 v0, v0, v66
	v_mul_f32_e32 v66, v14, v95
	v_and_b32_e32 v67, 0xffff0000, v167
	v_mul_f32_e32 v66, v66, v67
	v_cvt_pk_fp8_f32 v96, v0, v66 op_sel:[0,0,1]
	v_lshlrev_b32_e32 v0, 16, v114
	v_and_b32_e32 v94, 0xffff0000, v114
	v_lshlrev_b32_e32 v97, 16, v122
	global_store_dword v[24:25], v96, off offset:16
	s_nop 0
	v_fmac_f32_e32 v92, v6, v0
	v_fmac_f32_e32 v93, v6, v94
	v_fmac_f32_e32 v92, v12, v97
	v_fmac_f32_e32 v93, v12, v100
	v_mul_f32_e32 v0, v14, v92
	v_lshlrev_b32_e32 v95, 16, v115
	v_and_b32_e32 v96, 0xffff0000, v115
	v_fmac_f32_e32 v90, v6, v95
	v_fmac_f32_e32 v91, v6, v96
	v_fmac_f32_e32 v90, v12, v101
	v_fmac_f32_e32 v91, v12, v102
	v_lshlrev_b32_e32 v94, 16, v124
	v_and_b32_e32 v95, 0xffff0000, v124
	v_lshlrev_b32_e32 v96, 16, v125
	v_and_b32_e32 v97, 0xffff0000, v125
	s_waitcnt vmcnt(14)
	v_lshlrev_b32_e32 v92, 16, v168
	v_mul_f32_e32 v0, v0, v92
	v_mul_f32_e32 v92, v14, v93
	v_and_b32_e32 v66, 0xffff0000, v168
	v_mul_f32_e32 v66, v92, v66
	v_mov_b32_e32 v92, v1
	v_cvt_pk_fp8_f32 v92, v0, v66
	v_mul_f32_e32 v0, v14, v90
	v_lshlrev_b32_e32 v66, 16, v169
	v_mul_f32_e32 v0, v0, v66
	v_mul_f32_e32 v66, v14, v91
	v_and_b32_e32 v67, 0xffff0000, v169
	v_mul_f32_e32 v66, v66, v67
	v_cvt_pk_fp8_f32 v92, v0, v66 op_sel:[0,0,1]
	v_lshlrev_b32_e32 v90, 16, v116
	v_and_b32_e32 v91, 0xffff0000, v116
	v_fmac_f32_e32 v88, v6, v90
	global_store_dword v[24:25], v92, off offset:24
	s_nop 0
	v_fmac_f32_e32 v89, v6, v91
	v_fmac_f32_e32 v88, v12, v94
	v_fmac_f32_e32 v89, v12, v95
	v_mul_f32_e32 v88, v14, v88
	v_mul_f32_e32 v89, v14, v89
	v_mov_b32_e32 v0, v1
	v_lshlrev_b32_e32 v92, 16, v117
	v_and_b32_e32 v93, 0xffff0000, v117
	v_fmac_f32_e32 v86, v6, v92
	v_fmac_f32_e32 v87, v6, v93
	v_fmac_f32_e32 v86, v12, v96
	v_fmac_f32_e32 v87, v12, v97
	v_mul_f32_e32 v86, v14, v86
	v_mul_f32_e32 v87, v14, v87
	v_lshlrev_b32_e32 v92, 16, v133
	v_and_b32_e32 v93, 0xffff0000, v133
	s_waitcnt vmcnt(14)
; __device__ __forceinline__ float bf_lo(unsigned u) { return __uint_as_float(u << 16); }
; __device__ __forceinline__ float bf_hi(unsigned u) { return __uint_as_float(u & 0xffff0000u); }
; __device__ __forceinline__ void moba_own_item(LAS unsigned char* lds, const Ptrs& P, int b, int h, int j) {
;     ...
;     const float inv = __builtin_amdgcn_rcpf(L);
; #pragma unroll
;     for (int dt = 0; dt < 4; ++dt)
; #pragma unroll
;         for (int g4 = 0; g4 < 4; ++g4) { const int d = 32 * dt + 8 * g4 + 4 * hi;
;             const u32x2 gw = *(const u32x2*)(P.PA() + qrow * NA + C_GA + h * 128 + d);
;             const float i64 = inv * 16.f; int w8 = 0;
;             w8 = __builtin_amdgcn_cvt_pk_fp8_f32(o[dt][4 * g4] * i64 * bf_lo(gw.x), o[dt][4 * g4 + 1] * i64 * bf_hi(gw.x), w8, false); w8 = __builtin_amdgcn_cvt_pk_fp8_f32(o[dt][4 * g4 + 2] * i64 * bf_lo(gw.y), o[dt][4 * g4 + 3] * i64 * bf_hi(gw.y), w8, true);
;             *(unsigned*)(P.Y8() + qrow * 2048 + h * 128 + d) = (unsigned)w8; }
	v_lshlrev_b32_e32 v90, 16, v170
	v_and_b32_e32 v66, 0xffff0000, v170
	v_mul_f32_e32 v88, v88, v90
	v_mul_f32_e32 v66, v89, v66
	v_cvt_pk_fp8_f32 v0, v88, v66
	v_lshlrev_b32_e32 v91, 16, v171
	v_and_b32_e32 v66, 0xffff0000, v171
	v_mul_f32_e32 v67, v86, v91
	v_mul_f32_e32 v66, v87, v66
	v_cvt_pk_fp8_f32 v0, v67, v66 op_sel:[0,0,1]
	v_lshlrev_b32_e32 v86, 16, v118
	v_and_b32_e32 v87, 0xffff0000, v118
	v_lshlrev_b32_e32 v90, 16, v132
	global_store_dword v[24:25], v0, off offset:32
	s_nop 0
	v_and_b32_e32 v91, 0xffff0000, v132
	v_fmac_f32_e32 v84, v6, v86
	v_fmac_f32_e32 v85, v6, v87
	v_fmac_f32_e32 v84, v12, v90
	v_fmac_f32_e32 v85, v12, v91
	v_mul_f32_e32 v84, v14, v84
	v_mul_f32_e32 v85, v14, v85
	v_mov_b32_e32 v0, v1
	v_lshlrev_b32_e32 v88, 16, v119
	v_and_b32_e32 v89, 0xffff0000, v119
	v_fmac_f32_e32 v82, v6, v88
	v_fmac_f32_e32 v83, v6, v89
	v_fmac_f32_e32 v82, v12, v92
	v_fmac_f32_e32 v83, v12, v93
	v_mul_f32_e32 v82, v14, v82
	v_mul_f32_e32 v83, v14, v83
	v_lshlrev_b32_e32 v88, 16, v139
	v_and_b32_e32 v89, 0xffff0000, v139
	s_waitcnt vmcnt(14)
	v_lshlrev_b32_e32 v86, 16, v172
	v_and_b32_e32 v66, 0xffff0000, v172
	v_mul_f32_e32 v84, v84, v86
	v_mul_f32_e32 v66, v85, v66
	v_cvt_pk_fp8_f32 v0, v84, v66
	v_lshlrev_b32_e32 v87, 16, v173
	v_and_b32_e32 v66, 0xffff0000, v173
	v_mul_f32_e32 v67, v82, v87
	v_mul_f32_e32 v66, v83, v66
	v_cvt_pk_fp8_f32 v0, v67, v66 op_sel:[0,0,1]
	v_lshlrev_b32_e32 v82, 16, v108
	v_and_b32_e32 v83, 0xffff0000, v108
	v_lshlrev_b32_e32 v86, 16, v138
	global_store_dword v[24:25], v0, off offset:40
	s_nop 0
	v_and_b32_e32 v87, 0xffff0000, v138
	v_fmac_f32_e32 v80, v6, v82
	v_fmac_f32_e32 v81, v6, v83
	v_fmac_f32_e32 v80, v12, v86
	v_fmac_f32_e32 v81, v12, v87
	v_mul_f32_e32 v80, v14, v80
	v_mul_f32_e32 v81, v14, v81
	v_mov_b32_e32 v0, v1
	v_lshlrev_b32_e32 v84, 16, v109
	v_and_b32_e32 v85, 0xffff0000, v109
	v_fmac_f32_e32 v78, v6, v84
	v_fmac_f32_e32 v79, v6, v85
	v_fmac_f32_e32 v78, v12, v88
	v_fmac_f32_e32 v79, v12, v89
	v_mul_f32_e32 v78, v14, v78
	v_mul_f32_e32 v79, v14, v79
	s_waitcnt vmcnt(14)
	v_lshlrev_b32_e32 v82, 16, v174
	v_and_b32_e32 v66, 0xffff0000, v174
	v_mul_f32_e32 v80, v80, v82
	v_mul_f32_e32 v66, v81, v66
	v_cvt_pk_fp8_f32 v0, v80, v66
	v_lshlrev_b32_e32 v83, 16, v175
	v_and_b32_e32 v66, 0xffff0000, v175
	v_mul_f32_e32 v67, v78, v83
	v_mul_f32_e32 v66, v79, v66
	v_cvt_pk_fp8_f32 v0, v67, v66 op_sel:[0,0,1]
	v_lshlrev_b32_e32 v78, 16, v72
	v_and_b32_e32 v72, 0xffff0000, v72
	v_lshlrev_b32_e32 v80, 16, v98
	global_store_dword v[24:25], v0, off offset:48
	s_nop 0
	v_and_b32_e32 v81, 0xffff0000, v98
	v_fmac_f32_e32 v76, v6, v78
	v_fmac_f32_e32 v77, v6, v72
	v_lshlrev_b32_e32 v79, 16, v73
	v_and_b32_e32 v73, 0xffff0000, v73
	v_fmac_f32_e32 v76, v12, v80
	v_fmac_f32_e32 v77, v12, v81
	v_fmac_f32_e32 v75, v6, v73
	v_mul_f32_e32 v72, v14, v76
	v_mul_f32_e32 v73, v14, v77
	v_mov_b32_e32 v0, v1
	v_lshlrev_b32_e32 v82, 16, v99
	v_and_b32_e32 v83, 0xffff0000, v99
	v_fmac_f32_e32 v74, v6, v79
	v_fmac_f32_e32 v74, v12, v82
	v_fmac_f32_e32 v75, v12, v83
	v_mul_f32_e32 v74, v14, v74
	v_mul_f32_e32 v75, v14, v75
	s_waitcnt vmcnt(14)
	v_lshlrev_b32_e32 v76, 16, v176
	v_and_b32_e32 v66, 0xffff0000, v176
	v_mul_f32_e32 v72, v72, v76
	v_mul_f32_e32 v66, v73, v66
	v_cvt_pk_fp8_f32 v0, v72, v66
	v_lshlrev_b32_e32 v77, 16, v177
	v_and_b32_e32 v66, 0xffff0000, v177
	v_mul_f32_e32 v67, v74, v77
	v_mul_f32_e32 v66, v75, v66
	v_cvt_pk_fp8_f32 v0, v67, v66 op_sel:[0,0,1]
	v_lshlrev_b32_e32 v72, 16, v68
	v_and_b32_e32 v68, 0xffff0000, v68
	v_lshlrev_b32_e32 v74, 16, v70
	global_store_dword v[24:25], v0, off offset:56
	s_nop 0
	v_and_b32_e32 v70, 0xffff0000, v70
	v_fmac_f32_e32 v48, v6, v72
	v_fmac_f32_e32 v49, v6, v68
	v_lshlrev_b32_e32 v73, 16, v69
	v_and_b32_e32 v69, 0xffff0000, v69
	v_fmac_f32_e32 v48, v12, v74
	v_fmac_f32_e32 v49, v12, v70
	v_fmac_f32_e32 v47, v6, v69
	v_mul_f32_e32 v48, v14, v48
	v_mul_f32_e32 v49, v14, v49
	v_mov_b32_e32 v0, v1
	v_lshlrev_b32_e32 v75, 16, v71
	v_and_b32_e32 v71, 0xffff0000, v71
	v_fmac_f32_e32 v140, v6, v73
	v_fmac_f32_e32 v140, v12, v75
	v_fmac_f32_e32 v47, v12, v71
	v_mul_f32_e32 v68, v14, v140
	v_mul_f32_e32 v47, v14, v47
	s_waitcnt vmcnt(14)
	v_lshlrev_b32_e32 v69, 16, v178
	v_and_b32_e32 v66, 0xffff0000, v178
	v_mul_f32_e32 v48, v48, v69
	v_mul_f32_e32 v49, v49, v66
	v_cvt_pk_fp8_f32 v0, v48, v49
	v_lshlrev_b32_e32 v70, 16, v179
	v_and_b32_e32 v48, 0xffff0000, v179
	v_mul_f32_e32 v49, v68, v70
	v_mul_f32_e32 v47, v47, v48
	v_cvt_pk_fp8_f32 v0, v49, v47 op_sel:[0,0,1]
	v_lshlrev_b32_e32 v47, 16, v62
	v_and_b32_e32 v62, 0xffff0000, v62
	v_lshlrev_b32_e32 v67, 16, v64
	global_store_dword v[24:25], v0, off offset:64
	s_nop 0
	v_and_b32_e32 v64, 0xffff0000, v64
	v_fmac_f32_e32 v141, v6, v47
	v_fmac_f32_e32 v39, v6, v62
	v_lshlrev_b32_e32 v66, 16, v63
	v_and_b32_e32 v63, 0xffff0000, v63
	v_fmac_f32_e32 v141, v12, v67
	v_fmac_f32_e32 v39, v12, v64
	v_fmac_f32_e32 v41, v6, v63
	v_mul_f32_e32 v47, v14, v141
	v_mul_f32_e32 v39, v14, v39
	v_mov_b32_e32 v0, v1
	v_lshlrev_b32_e32 v68, 16, v65
	v_and_b32_e32 v65, 0xffff0000, v65
	v_fmac_f32_e32 v142, v6, v66
	v_fmac_f32_e32 v142, v12, v68
	v_fmac_f32_e32 v41, v12, v65
	v_mul_f32_e32 v62, v14, v142
	v_mul_f32_e32 v41, v14, v41
	s_waitcnt vmcnt(14)
; __device__ __forceinline__ float bf_lo(unsigned u) { return __uint_as_float(u << 16); }
; __device__ __forceinline__ float bf_hi(unsigned u) { return __uint_as_float(u & 0xffff0000u); }
; __device__ __forceinline__ void moba_own_item(LAS unsigned char* lds, const Ptrs& P, int b, int h, int j) {
;     ...
;     const float inv = __builtin_amdgcn_rcpf(L);
; #pragma unroll
;     for (int dt = 0; dt < 4; ++dt)
; #pragma unroll
;         for (int g4 = 0; g4 < 4; ++g4) { const int d = 32 * dt + 8 * g4 + 4 * hi;
;             const u32x2 gw = *(const u32x2*)(P.PA() + qrow * NA + C_GA + h * 128 + d);
;             const float i64 = inv * 16.f; int w8 = 0;
;             w8 = __builtin_amdgcn_cvt_pk_fp8_f32(o[dt][4 * g4] * i64 * bf_lo(gw.x), o[dt][4 * g4 + 1] * i64 * bf_hi(gw.x), w8, false); w8 = __builtin_amdgcn_cvt_pk_fp8_f32(o[dt][4 * g4 + 2] * i64 * bf_lo(gw.y), o[dt][4 * g4 + 3] * i64 * bf_hi(gw.y), w8, true);
;             *(unsigned*)(P.Y8() + qrow * 2048 + h * 128 + d) = (unsigned)w8; }
;     __syncthreads();
	v_lshlrev_b32_e32 v63, 16, v180
	v_and_b32_e32 v48, 0xffff0000, v180
	v_mul_f32_e32 v47, v47, v63
	v_mul_f32_e32 v39, v39, v48
	v_cvt_pk_fp8_f32 v0, v47, v39
	v_lshlrev_b32_e32 v64, 16, v181
	v_and_b32_e32 v39, 0xffff0000, v181
	v_mul_f32_e32 v47, v62, v64
	v_mul_f32_e32 v39, v41, v39
	v_cvt_pk_fp8_f32 v0, v47, v39 op_sel:[0,0,1]
	v_lshlrev_b32_e32 v39, 16, v58
	v_and_b32_e32 v41, 0xffff0000, v58
	v_lshlrev_b32_e32 v47, 16, v59
	global_store_dword v[24:25], v0, off offset:72
	s_nop 0
	v_and_b32_e32 v58, 0xffff0000, v59
	v_lshlrev_b32_e32 v59, 16, v60
	v_and_b32_e32 v60, 0xffff0000, v60
	v_lshlrev_b32_e32 v62, 16, v61
	v_fmac_f32_e32 v40, v6, v39
	v_fmac_f32_e32 v31, v6, v41
	v_fmac_f32_e32 v46, v6, v47
	v_fmac_f32_e32 v40, v12, v59
	v_fmac_f32_e32 v31, v12, v60
	v_fmac_f32_e32 v46, v12, v62
	v_mul_f32_e32 v39, v14, v40
	v_mul_f32_e32 v31, v14, v31
	v_mul_f32_e32 v40, v14, v46
	v_mov_b32_e32 v0, v1
	v_and_b32_e32 v61, 0xffff0000, v61
	v_fmac_f32_e32 v27, v6, v58
	v_fmac_f32_e32 v27, v12, v61
	v_mul_f32_e32 v27, v14, v27
	s_waitcnt vmcnt(14)
	v_lshlrev_b32_e32 v41, 16, v182
	v_and_b32_e32 v46, 0xffff0000, v182
	v_mul_f32_e32 v39, v39, v41
	v_mul_f32_e32 v31, v31, v46
	v_cvt_pk_fp8_f32 v0, v39, v31
	v_lshlrev_b32_e32 v47, 16, v183
	v_and_b32_e32 v31, 0xffff0000, v183
	v_mul_f32_e32 v39, v40, v47
	v_mul_f32_e32 v27, v27, v31
	v_cvt_pk_fp8_f32 v0, v39, v27 op_sel:[0,0,1]
	v_lshlrev_b32_e32 v27, 16, v54
	v_and_b32_e32 v31, 0xffff0000, v54
	v_lshlrev_b32_e32 v39, 16, v55
	global_store_dword v[24:25], v0, off offset:80
	s_nop 0
	v_lshlrev_b32_e32 v47, 16, v56
	v_and_b32_e32 v48, 0xffff0000, v56
	v_lshlrev_b32_e32 v49, 16, v57
	v_fmac_f32_e32 v30, v6, v27
	v_fmac_f32_e32 v21, v6, v31
	v_fmac_f32_e32 v38, v6, v39
	v_fmac_f32_e32 v30, v12, v47
	v_fmac_f32_e32 v21, v12, v48
	v_fmac_f32_e32 v38, v12, v49
	v_mul_f32_e32 v27, v14, v30
	v_mul_f32_e32 v21, v14, v21
	v_mul_f32_e32 v30, v14, v38
	v_mov_b32_e32 v0, v1
	v_and_b32_e32 v46, 0xffff0000, v55
	v_and_b32_e32 v54, 0xffff0000, v57
	v_fmac_f32_e32 v19, v6, v46
	v_fmac_f32_e32 v19, v12, v54
	v_mul_f32_e32 v19, v14, v19
	v_and_b32_e32 v46, 0xffff0000, v53
	s_waitcnt vmcnt(14)
	v_lshlrev_b32_e32 v31, 16, v184
	v_and_b32_e32 v38, 0xffff0000, v184
	v_mul_f32_e32 v27, v27, v31
	v_mul_f32_e32 v21, v21, v38
	v_cvt_pk_fp8_f32 v0, v27, v21
	v_lshlrev_b32_e32 v39, 16, v185
	v_and_b32_e32 v21, 0xffff0000, v185
	v_mul_f32_e32 v27, v30, v39
	v_mul_f32_e32 v19, v19, v21
	v_cvt_pk_fp8_f32 v0, v27, v19 op_sel:[0,0,1]
	v_lshlrev_b32_e32 v19, 16, v50
	v_and_b32_e32 v21, 0xffff0000, v50
	v_lshlrev_b32_e32 v27, 16, v51
	global_store_dword v[24:25], v0, off offset:88
	s_nop 0
	v_lshlrev_b32_e32 v39, 16, v52
	v_and_b32_e32 v40, 0xffff0000, v52
	v_lshlrev_b32_e32 v41, 16, v53
	v_fmac_f32_e32 v20, v6, v19
	v_fmac_f32_e32 v17, v6, v21
	v_fmac_f32_e32 v26, v6, v27
	v_fmac_f32_e32 v20, v12, v39
	v_fmac_f32_e32 v17, v12, v40
	v_fmac_f32_e32 v26, v12, v41
	v_mul_f32_e32 v19, v14, v20
	v_mul_f32_e32 v17, v14, v17
	v_mul_f32_e32 v20, v14, v26
	v_mov_b32_e32 v0, v1
	v_and_b32_e32 v38, 0xffff0000, v51
	v_fmac_f32_e32 v15, v6, v38
	v_fmac_f32_e32 v15, v12, v46
	v_mul_f32_e32 v15, v14, v15
	v_and_b32_e32 v38, 0xffff0000, v45
	s_waitcnt vmcnt(14)
	v_lshlrev_b32_e32 v21, 16, v186
	v_and_b32_e32 v26, 0xffff0000, v186
	v_mul_f32_e32 v19, v19, v21
	v_mul_f32_e32 v17, v17, v26
	v_cvt_pk_fp8_f32 v0, v19, v17
	v_lshlrev_b32_e32 v27, 16, v187
	v_and_b32_e32 v17, 0xffff0000, v187
	v_mul_f32_e32 v19, v20, v27
	v_mul_f32_e32 v15, v15, v17
	v_cvt_pk_fp8_f32 v0, v19, v15 op_sel:[0,0,1]
	v_lshlrev_b32_e32 v15, 16, v42
	v_and_b32_e32 v17, 0xffff0000, v42
	v_lshlrev_b32_e32 v19, 16, v43
	global_store_dword v[24:25], v0, off offset:96
	s_nop 0
	v_lshlrev_b32_e32 v27, 16, v44
	v_and_b32_e32 v30, 0xffff0000, v44
	v_lshlrev_b32_e32 v31, 16, v45
	v_fmac_f32_e32 v16, v6, v15
	v_fmac_f32_e32 v13, v6, v17
	v_fmac_f32_e32 v18, v6, v19
	v_fmac_f32_e32 v16, v12, v27
	v_fmac_f32_e32 v13, v12, v30
	v_fmac_f32_e32 v18, v12, v31
	v_mul_f32_e32 v15, v14, v16
	v_mul_f32_e32 v13, v14, v13
	v_mul_f32_e32 v16, v14, v18
	v_mov_b32_e32 v0, v1
	v_and_b32_e32 v26, 0xffff0000, v43
	v_fmac_f32_e32 v11, v6, v26
	v_fmac_f32_e32 v11, v12, v38
	v_mul_f32_e32 v11, v14, v11
	v_and_b32_e32 v26, 0xffff0000, v37
	s_waitcnt vmcnt(14)
	v_lshlrev_b32_e32 v17, 16, v188
	v_and_b32_e32 v18, 0xffff0000, v188
	v_mul_f32_e32 v15, v15, v17
	v_mul_f32_e32 v13, v13, v18
	v_cvt_pk_fp8_f32 v0, v15, v13
	v_lshlrev_b32_e32 v19, 16, v189
	v_and_b32_e32 v13, 0xffff0000, v189
	v_mul_f32_e32 v15, v16, v19
	v_mul_f32_e32 v11, v11, v13
	v_cvt_pk_fp8_f32 v0, v15, v11 op_sel:[0,0,1]
	v_lshlrev_b32_e32 v11, 16, v32
	v_and_b32_e32 v13, 0xffff0000, v32
	v_lshlrev_b32_e32 v19, 16, v36
	global_store_dword v[24:25], v0, off offset:104
	s_nop 0
	v_and_b32_e32 v20, 0xffff0000, v36
	v_fmac_f32_e32 v8, v6, v11
	v_fmac_f32_e32 v9, v6, v13
	v_fmac_f32_e32 v8, v12, v19
	v_fmac_f32_e32 v9, v12, v20
	v_mul_f32_e32 v8, v14, v8
	v_mul_f32_e32 v9, v14, v9
	v_mov_b32_e32 v0, v1
	v_lshlrev_b32_e32 v15, 16, v33
	v_and_b32_e32 v18, 0xffff0000, v33
	v_lshlrev_b32_e32 v21, 16, v37
	v_fmac_f32_e32 v10, v6, v15
	v_fmac_f32_e32 v7, v6, v18
	v_fmac_f32_e32 v10, v12, v21
	v_fmac_f32_e32 v7, v12, v26
	v_mul_f32_e32 v10, v14, v10
	v_mul_f32_e32 v7, v14, v7
	v_and_b32_e32 v18, 0xffff0000, v29
	s_waitcnt vmcnt(14)
	v_lshlrev_b32_e32 v11, 16, v190
	v_and_b32_e32 v13, 0xffff0000, v190
	v_mul_f32_e32 v8, v8, v11
	v_mul_f32_e32 v9, v9, v13
	v_cvt_pk_fp8_f32 v0, v8, v9
	v_lshlrev_b32_e32 v15, 16, v191
	v_and_b32_e32 v8, 0xffff0000, v191
	v_mul_f32_e32 v9, v10, v15
	v_mul_f32_e32 v7, v7, v8
	v_cvt_pk_fp8_f32 v0, v9, v7 op_sel:[0,0,1]
	v_lshlrev_b32_e32 v7, 16, v22
	v_and_b32_e32 v10, 0xffff0000, v22
	v_lshlrev_b32_e32 v15, 16, v28
	global_store_dword v[24:25], v0, off offset:112
	s_nop 0
	v_and_b32_e32 v16, 0xffff0000, v28
	v_fmac_f32_e32 v4, v6, v7
	v_fmac_f32_e32 v5, v6, v10
	v_lshlrev_b32_e32 v11, 16, v23
	v_and_b32_e32 v13, 0xffff0000, v23
	v_fmac_f32_e32 v4, v12, v15
	v_fmac_f32_e32 v5, v12, v16
	v_fmac_f32_e32 v2, v6, v11
	v_fmac_f32_e32 v3, v6, v13
	v_mul_f32_e32 v4, v14, v4
	v_mul_f32_e32 v5, v14, v5
	v_mov_b32_e32 v0, v1
	v_lshlrev_b32_e32 v17, 16, v29
	v_fmac_f32_e32 v2, v12, v17
	v_fmac_f32_e32 v3, v12, v18
	v_mul_f32_e32 v2, v14, v2
	v_mul_f32_e32 v3, v14, v3
	s_waitcnt vmcnt(14)
	v_lshlrev_b32_e32 v6, 16, v192
	v_and_b32_e32 v7, 0xffff0000, v192
	v_mul_f32_e32 v4, v4, v6
	v_mul_f32_e32 v5, v5, v7
	v_cvt_pk_fp8_f32 v0, v4, v5
	v_lshlrev_b32_e32 v8, 16, v193
	v_and_b32_e32 v4, 0xffff0000, v193
	v_mul_f32_e32 v2, v2, v8
	v_mul_f32_e32 v3, v3, v4
	v_cvt_pk_fp8_f32 v0, v2, v3 op_sel:[0,0,1]
	v_mov_b32_e32 v3, v163
	global_store_dword v[24:25], v0, off offset:120
	s_barrier
; __device__ __forceinline__ int t5_bucket(int n) {
;     if (n < 16) return n;
;     int b = 16;
;     b += (n >= 19); b += (n >= 21); b += (n >= 24); b += (n >= 27); b += (n >= 31); b += (n >= 35); b += (n >= 40); b += (n >= 46);
;     b += (n >= 52); b += (n >= 59); b += (n >= 67); b += (n >= 77); b += (n >= 87); b += (n >= 99); b += (n >= 113);
;     return b;
; }
; __device__ __forceinline__ void moba_own_item(LAS unsigned char* lds, const Ptrs& P, int b, int h, int j) {
;     ...
;     if (tid < 129) lut[tid] = P.rpe[t5_bucket(tid) * 24 + h] * LOG2E;
	s_nop 0
	v_readfirstlane_b32 s58, v3
	v_cmp_gt_i32_e32 vcc, s35, v3
	s_and_saveexec_b64 s[0:1], vcc
	s_cbranch_execz .LBB0_1873
	v_cmp_lt_i32_e32 vcc, 15, v3
	v_mov_b32_e32 v0, v3
	s_and_saveexec_b64 s[4:5], vcc
	s_cbranch_execz .LBB0_1872
	v_cmp_lt_u32_e32 vcc, 18, v3
	s_nop 1
	v_cndmask_b32_e64 v0, 16, 17, vcc
	v_cmp_lt_u32_e32 vcc, 20, v3
	s_nop 1
	v_cndmask_b32_e64 v2, 0, 1, vcc
	v_cmp_lt_u32_e32 vcc, 23, v3
	s_nop 1
	v_addc_co_u32_e32 v0, vcc, v0, v2, vcc
	v_cmp_lt_u32_e32 vcc, 26, v3
	s_nop 1
	v_cndmask_b32_e64 v2, 0, 1, vcc
	v_cmp_lt_u32_e32 vcc, 30, v3
	s_nop 1
	v_addc_co_u32_e32 v0, vcc, v0, v2, vcc
	v_cmp_lt_u32_e32 vcc, 34, v3
	s_nop 1
	v_cndmask_b32_e64 v2, 0, 1, vcc
	v_cmp_lt_u32_e32 vcc, 39, v3
	s_nop 1
	v_addc_co_u32_e32 v0, vcc, v0, v2, vcc
	v_cmp_lt_u32_e32 vcc, 45, v3
	s_nop 1
	v_cndmask_b32_e64 v2, 0, 1, vcc
	v_cmp_lt_u32_e32 vcc, 51, v3
	s_nop 1
	v_addc_co_u32_e32 v0, vcc, v0, v2, vcc
	v_cmp_lt_u32_e32 vcc, 58, v3
	s_nop 1
	v_cndmask_b32_e64 v2, 0, 1, vcc
	v_cmp_lt_u32_e32 vcc, s36, v3
	s_nop 1
	v_addc_co_u32_e32 v0, vcc, v0, v2, vcc
	v_cmp_lt_u32_e32 vcc, s37, v3
	s_nop 1
	v_cndmask_b32_e64 v2, 0, 1, vcc
	v_cmp_lt_u32_e32 vcc, s38, v3
	s_nop 1
	v_addc_co_u32_e32 v0, vcc, v0, v2, vcc
	v_cmp_lt_u32_e32 vcc, s39, v3
	s_nop 1
	v_cndmask_b32_e64 v2, 0, 1, vcc
	v_cmp_lt_u32_e32 vcc, s40, v3
	s_nop 1
	v_addc_co_u32_e32 v0, vcc, v0, v2, vcc
